# attention loops: packed v_pk_add_f32 (hook bias adds) split into scalar v_add_f32 pairs (instruction selection, bit-identical)
# baseline (speedup 1.0000x reference)
; template<int MODE> __device__ __forceinline__ void hook(f32x16&p0,f32x16&p1,int t,int NT,int qrel,int hi,lds_fptr tab,int dbase,int ibase){
;     ...
;     const lds_fptr tb=tab+64*t+4*hi;
;     #pragma unroll
;     for(int g=0;g<4;++g){ const f32x4a a=*(const __attribute__((address_space(3))) f32x4a*)(tb+8*g); const f32x4a c=*(const __attribute__((address_space(3))) f32x4a*)(tb+32+8*g);
;       p0[4*g+0]+=a.x;p0[4*g+1]+=a.y;p0[4*g+2]+=a.z;p0[4*g+3]+=a.w; p1[4*g+0]+=c.x;p1[4*g+1]+=c.y;p1[4*g+2]+=c.z;p1[4*g+3]+=c.w; }
.LBB0_755:
	v_add_u32_e32 v0, s6, v249
	ds_read_b64_tr_b16 v[192:193], v0 offset:24576
	ds_read_b64_tr_b16 v[194:195], v0 offset:25088
	v_add_f32_e32 v2, v80, v81
	v_add_f32_e32 v2, v82, v2
	v_add_f32_e32 v2, v83, v2
	v_add_f32_e32 v2, v84, v2
	v_add_f32_e32 v2, v85, v2
	v_cvt_pk_bf16_f32 v156, v80, v81
	v_cvt_pk_bf16_f32 v157, v82, v83
	s_waitcnt lgkmcnt(9)
	v_mfma_f32_32x32x16_bf16 v[112:127], v[188:191], v[140:143], v[48:63]
	ds_read_b64_tr_b16 v[188:189], v0 offset:28672
	ds_read_b64_tr_b16 v[190:191], v0 offset:29184
	v_add_f32_e32 v2, v86, v2
	v_add_f32_e32 v2, v87, v2
	v_add_f32_e32 v2, v88, v2
	v_add_f32_e32 v6, v89, v2
	v_cvt_pk_bf16_f32 v158, v84, v85
	v_cvt_pk_bf16_f32 v159, v86, v87
	s_waitcnt lgkmcnt(10)
	v_mfma_f32_32x32x16_bf16 v[96:111], v[184:187], v[140:143], v[48:63]
	ds_read_b64_tr_b16 v[2:3], v0 offset:25600
	ds_read_b64_tr_b16 v[4:5], v0 offset:26112
	v_add_f32_e32 v6, v90, v6
	v_add_f32_e32 v6, v91, v6
	v_add_f32_e32 v6, v92, v6
	v_add_f32_e32 v10, v93, v6
	v_cvt_pk_bf16_f32 v152, v88, v89
	v_cvt_pk_bf16_f32 v153, v90, v91
	s_waitcnt lgkmcnt(11)
	v_mfma_f32_32x32x16_bf16 v[112:127], v[180:183], v[136:139], v[112:127]
	ds_read_b64_tr_b16 v[6:7], v0 offset:29696
	ds_read_b64_tr_b16 v[8:9], v0 offset:30208
	v_add_f32_e32 v10, v94, v10
	v_add_f32_e32 v10, v95, v10
	v_add_f32_e32 v10, v64, v10
	v_add_f32_e32 v14, v65, v10
	v_cvt_pk_bf16_f32 v154, v92, v93
	v_cvt_pk_bf16_f32 v155, v94, v95
	s_waitcnt lgkmcnt(12)
	v_mfma_f32_32x32x16_bf16 v[96:111], v[176:179], v[136:139], v[96:111]
	ds_read_b64_tr_b16 v[10:11], v0 offset:26624
	ds_read_b64_tr_b16 v[12:13], v0 offset:27136
	v_add_f32_e32 v14, v66, v14
	v_add_f32_e32 v14, v67, v14
	v_add_f32_e32 v14, v68, v14
	v_add_f32_e32 v14, v69, v14
	v_cvt_pk_bf16_f32 v148, v64, v65
	v_cvt_pk_bf16_f32 v149, v66, v67
	s_waitcnt lgkmcnt(13)
	v_mfma_f32_32x32x16_bf16 v[112:127], v[172:175], v[132:135], v[112:127]
	ds_read_b64_tr_b16 v[172:173], v0 offset:30720
	ds_read_b64_tr_b16 v[174:175], v0 offset:31232
	v_add_f32_e32 v14, v70, v14
	v_add_f32_e32 v14, v71, v14
	v_add_f32_e32 v14, v72, v14
	v_add_f32_e32 v14, v73, v14
	v_cvt_pk_bf16_f32 v150, v68, v69
	v_cvt_pk_bf16_f32 v151, v70, v71
	s_waitcnt lgkmcnt(14)
	v_mfma_f32_32x32x16_bf16 v[96:111], v[168:171], v[132:135], v[96:111]
	ds_read_b64_tr_b16 v[168:169], v0 offset:27648
	ds_read_b64_tr_b16 v[170:171], v0 offset:28160
	v_add_f32_e32 v14, v74, v14
	v_add_f32_e32 v14, v75, v14
	v_add_f32_e32 v14, v76, v14
	v_add_f32_e32 v14, v77, v14
	v_cvt_pk_bf16_f32 v144, v72, v73
	v_cvt_pk_bf16_f32 v145, v74, v75
	s_waitcnt lgkmcnt(14)
	v_mfma_f32_32x32x16_bf16 v[112:127], v[164:167], v[128:131], v[112:127]
	ds_read_b64_tr_b16 v[164:165], v0 offset:31744
	ds_read_b64_tr_b16 v[166:167], v0 offset:32256
	v_add_f32_e32 v0, v78, v14
	v_add_f32_e32 v0, v79, v0
	v_add_f32_e32 v0, 0, v0
	v_cvt_pk_bf16_f32 v146, v76, v77
	v_cvt_pk_bf16_f32 v147, v78, v79
	v_mfma_f32_32x32x16_bf16 v[96:111], v[160:163], v[128:131], v[96:111]
	v_lshl_add_u64 v[14:15], v[204:205], 0, s[78:79]
	v_lshl_add_u64 v[64:65], v[14:15], 0, s[46:47]
	s_add_i32 s6, s1, s62
	s_mov_b32 s7, m0
	s_mov_b32 m0, s6
	s_nop 0
	global_load_lds_dwordx4 v[64:65], off
	s_mov_b32 m0, s7
	v_lshl_add_u64 v[220:221], v[206:207], 0, s[78:79]
	v_lshl_add_u64 v[64:65], v[220:221], 0, s[74:75]
	s_add_i32 s6, s81, s97
	s_mov_b32 s7, m0
	s_mov_b32 m0, s6
	s_nop 0
	global_load_lds_dwordx4 v[64:65], off
	s_mov_b32 m0, s7
	ds_read_b128 v[64:67], v252
	ds_read_b128 v[68:71], v252 offset:32
	ds_read_b128 v[72:75], v252 offset:64
	ds_read_b128 v[76:79], v252 offset:96
	ds_read_b128 v[160:163], v252 offset:128
	ds_read_b128 v[176:179], v252 offset:160
	ds_read_b128 v[180:183], v252 offset:192
	ds_read_b128 v[184:187], v252 offset:224
	s_add_i32 s80, s55, s41
	s_add_i32 s6, s80, 1
	s_waitcnt lgkmcnt(4)
	v_add_f32_e32 v92, v124, v76
	v_add_f32_e32 v93, v125, v77
	v_add_f32_e32 v88, v120, v72
	v_add_f32_e32 v89, v121, v73
	v_add_f32_e32 v84, v116, v68
	v_add_f32_e32 v85, v117, v69
	v_add_f32_e32 v94, v126, v78
	v_add_f32_e32 v95, v127, v79
	v_add_f32_e32 v90, v122, v74
	v_add_f32_e32 v91, v123, v75
	v_add_f32_e32 v86, v118, v70
	v_add_f32_e32 v87, v119, v71
	v_add_f32_e32 v82, v114, v66
	v_add_f32_e32 v83, v115, v67
	v_add_f32_e32 v80, v112, v64
	v_add_f32_e32 v81, v113, v65
	s_waitcnt lgkmcnt(0)
	v_add_f32_e32 v76, v108, v184
	v_add_f32_e32 v77, v109, v185
	v_add_f32_e32 v72, v104, v180
	v_add_f32_e32 v73, v105, v181
	v_add_f32_e32 v68, v100, v176
	v_add_f32_e32 v69, v101, v177
	v_add_f32_e32 v78, v110, v186
	v_add_f32_e32 v79, v111, v187
	v_add_f32_e32 v74, v106, v182
	v_add_f32_e32 v75, v107, v183
	v_add_f32_e32 v70, v102, v178
	v_add_f32_e32 v71, v103, v179
	v_add_f32_e32 v66, v98, v162
	v_add_f32_e32 v67, v99, v163
	s_cmp_lt_i32 s6, 0
	v_add_f32_e32 v64, v96, v160
	v_add_f32_e32 v65, v97, v161
	s_cbranch_scc1 .LBB0_759
; __device__ __forceinline__ void cmask(f32x16&p0,f32x16&p1,int jb,int qrel,int hi){
;   const float NEG=-INFINITY; int kb=64*jb+4*hi;
;   #pragma unroll
;   for(int r=0;r<16;++r){int kv=kb+(r&3)+8*(r>>2); if(kv>qrel)p0[r]=NEG; if(kv+32>qrel)p1[r]=NEG;}
; }
	v_add_u32_e32 v97, 0xffffffa5, v251
	v_add_u32_e32 v96, 0xffffff85, v251
	v_cmp_le_i32_e64 s[6:7], v97, v246
	v_cmp_le_i32_e32 vcc, v96, v246
	s_nop 0
	v_cndmask_b32_e64 v64, v238, v64, s[6:7]
	v_cmp_lt_i32_e64 s[6:7], v96, v246
	v_add_u32_e32 v96, 0xffffffa6, v251
	v_cmp_le_i32_e64 s[8:9], v96, v246
	v_add_u32_e32 v96, 0xffffff87, v251
	s_nop 0
	v_cndmask_b32_e64 v65, v238, v65, s[8:9]
	v_cmp_le_i32_e64 s[8:9], v96, v246
	v_add_u32_e32 v96, 0xffffffa7, v251
	v_cmp_le_i32_e64 s[10:11], v96, v246
	v_add_u32_e32 v96, 0xffffff88, v251
	s_nop 0
	v_cndmask_b32_e64 v66, v238, v66, s[10:11]
	v_cmp_le_i32_e64 s[10:11], v96, v246
	v_add_u32_e32 v96, 0xffffffa8, v251
	v_cmp_le_i32_e64 s[12:13], v96, v246
	v_add_u32_e32 v96, 0xffffff8d, v251
	s_nop 0
	v_cndmask_b32_e64 v67, v238, v67, s[12:13]
	v_cmp_le_i32_e64 s[12:13], v96, v246
	v_add_u32_e32 v96, 0xffffffad, v251
	v_cmp_le_i32_e64 s[14:15], v96, v246
	v_add_u32_e32 v96, 0xffffff8e, v251
	s_nop 0
	v_cndmask_b32_e64 v68, v238, v68, s[14:15]
	v_cmp_le_i32_e64 s[14:15], v96, v246
	v_add_u32_e32 v96, 0xffffffae, v251
	v_cmp_le_i32_e64 s[16:17], v96, v246
	v_add_u32_e32 v96, 0xffffff8f, v251
	s_nop 0
	v_cndmask_b32_e64 v69, v238, v69, s[16:17]
	v_cmp_le_i32_e64 s[16:17], v96, v246
	v_add_u32_e32 v96, 0xffffffaf, v251
	v_cmp_le_i32_e64 s[18:19], v96, v246
	v_add_u32_e32 v96, 0xffffff90, v251
	s_nop 0
	v_cndmask_b32_e64 v70, v238, v70, s[18:19]
	v_cmp_le_i32_e64 s[18:19], v96, v246
	v_add_u32_e32 v96, 0xffffffb0, v251
	v_cmp_le_i32_e64 s[20:21], v96, v246
	v_add_u32_e32 v96, 0xffffff95, v251
	s_nop 0
	v_cndmask_b32_e64 v71, v238, v71, s[20:21]
	v_cmp_le_i32_e64 s[20:21], v96, v246
	v_add_u32_e32 v96, 0xffffffb5, v251
	v_cmp_le_i32_e64 s[22:23], v96, v246
	v_add_u32_e32 v96, 0xffffff96, v251
	s_nop 0
	v_cndmask_b32_e64 v72, v238, v72, s[22:23]
	v_cmp_le_i32_e64 s[22:23], v96, v246
	v_add_u32_e32 v96, 0xffffffb6, v251
	v_cmp_le_i32_e64 s[24:25], v96, v246
	v_add_u32_e32 v96, 0xffffff97, v251
	s_nop 0
	v_cndmask_b32_e64 v73, v238, v73, s[24:25]
	v_cmp_le_i32_e64 s[24:25], v96, v246
	v_add_u32_e32 v96, 0xffffffb7, v251
	v_cmp_le_i32_e64 s[26:27], v96, v246
	v_add_u32_e32 v96, 0xffffff98, v251
	s_nop 0
	v_cndmask_b32_e64 v74, v238, v74, s[26:27]
	v_cmp_le_i32_e64 s[26:27], v96, v246
	v_add_u32_e32 v96, 0xffffffb8, v251
	v_cmp_le_i32_e64 s[28:29], v96, v246
	v_add_u32_e32 v96, 0xffffff9d, v251
	s_nop 0
	v_cndmask_b32_e64 v75, v238, v75, s[28:29]
	v_cmp_le_i32_e64 s[28:29], v96, v246
	v_add_u32_e32 v96, 0xffffffbd, v251
	v_cmp_le_i32_e64 s[30:31], v96, v246
	v_add_u32_e32 v96, 0xffffff9e, v251
	s_nop 0
	v_cndmask_b32_e64 v76, v238, v76, s[30:31]
	v_cmp_le_i32_e64 s[30:31], v96, v246
	v_add_u32_e32 v96, 0xffffffbe, v251
	v_cmp_le_i32_e64 s[34:35], v96, v246
	v_add_u32_e32 v96, 0xffffff9f, v251
	s_nop 0
	v_cndmask_b32_e64 v77, v238, v77, s[34:35]
	v_cmp_le_i32_e64 s[34:35], v96, v246
	v_add_u32_e32 v96, 0xffffffbf, v251
	v_cmp_le_i32_e64 s[36:37], v96, v246
	v_add_u32_e32 v96, 0xffffffa0, v251
	s_nop 0
	v_cndmask_b32_e64 v78, v238, v78, s[36:37]
	v_cmp_le_i32_e64 s[36:37], v96, v246
	v_subrev_u32_e32 v96, 64, v251
	v_cmp_gt_i32_e64 s[38:39], v96, v246
	s_and_saveexec_b64 s[44:45], s[38:39]
	v_mov_b32_e32 v79, s73
	s_or_b64 exec, exec, s[44:45]
	v_cndmask_b32_e64 v81, v238, v81, s[6:7]
	v_cndmask_b32_e32 v80, v238, v80, vcc
	v_cndmask_b32_e64 v82, v238, v82, s[8:9]
	v_cndmask_b32_e64 v83, v238, v83, s[10:11]
	v_cndmask_b32_e64 v84, v238, v84, s[12:13]
	v_cndmask_b32_e64 v85, v238, v85, s[14:15]
	v_cndmask_b32_e64 v86, v238, v86, s[16:17]
	v_cndmask_b32_e64 v87, v238, v87, s[18:19]
	v_cndmask_b32_e64 v88, v238, v88, s[20:21]
	v_cndmask_b32_e64 v89, v238, v89, s[22:23]
	v_cndmask_b32_e64 v90, v238, v90, s[24:25]
	v_cndmask_b32_e64 v91, v238, v91, s[26:27]
	v_cndmask_b32_e64 v92, v238, v92, s[28:29]
	v_cndmask_b32_e64 v93, v238, v93, s[30:31]
	v_cndmask_b32_e64 v94, v238, v94, s[34:35]
	v_cndmask_b32_e64 v95, v238, v95, s[36:37]

; template<int MODE> __device__ __forceinline__ void hook(f32x16&p0,f32x16&p1,int t,int NT,int qrel,int hi,lds_fptr tab,int dbase,int ibase){
;     ...
;     const lds_fptr tb=tab+64*t+4*hi;
;     #pragma unroll
;     for(int g=0;g<4;++g){ const f32x4a a=*(const __attribute__((address_space(3))) f32x4a*)(tb+8*g); const f32x4a c=*(const __attribute__((address_space(3))) f32x4a*)(tb+32+8*g);
;       p0[4*g+0]+=a.x;p0[4*g+1]+=a.y;p0[4*g+2]+=a.z;p0[4*g+3]+=a.w; p1[4*g+0]+=c.x;p1[4*g+1]+=c.y;p1[4*g+2]+=c.z;p1[4*g+3]+=c.w; }
.LBB0_762:
	s_add_i32 s6, s81, 0x2000
	s_cmpk_lg_i32 s81, 0x4000
	s_cselect_b32 s63, s6, 0
	v_add_u32_e32 v168, s1, v249
	ds_read_b64_tr_b16 v[164:165], v168 offset:24576
	ds_read_b64_tr_b16 v[166:167], v168 offset:25088
	v_add_f32_e32 v2, v80, v81
	v_add_f32_e32 v2, v82, v2
	v_add_f32_e32 v2, v83, v2
	v_add_f32_e32 v2, v84, v2
	v_add_f32_e32 v2, v85, v2
	v_cvt_pk_bf16_f32 v156, v80, v81
	v_cvt_pk_bf16_f32 v157, v82, v83
	s_waitcnt lgkmcnt(9)
	v_mfma_f32_32x32x16_bf16 v[112:127], v[96:99], v[140:143], v[48:63]
	ds_read_b64_tr_b16 v[160:161], v168 offset:28672
	ds_read_b64_tr_b16 v[162:163], v168 offset:29184
	v_add_f32_e32 v2, v86, v2
	v_add_f32_e32 v2, v87, v2
	v_add_f32_e32 v2, v88, v2
	v_add_f32_e32 v6, v89, v2
	v_cvt_pk_bf16_f32 v158, v84, v85
	v_cvt_pk_bf16_f32 v159, v86, v87
	s_waitcnt lgkmcnt(10)
	v_mfma_f32_32x32x16_bf16 v[96:111], v[196:199], v[140:143], v[48:63]
	ds_read_b64_tr_b16 v[2:3], v168 offset:25600
	ds_read_b64_tr_b16 v[4:5], v168 offset:26112
	v_add_f32_e32 v6, v90, v6
	v_add_f32_e32 v6, v91, v6
	v_add_f32_e32 v6, v92, v6
	v_add_f32_e32 v10, v93, v6
	v_cvt_pk_bf16_f32 v152, v88, v89
	v_cvt_pk_bf16_f32 v153, v90, v91
	s_waitcnt lgkmcnt(11)
	v_mfma_f32_32x32x16_bf16 v[112:127], v[200:203], v[136:139], v[112:127]
	ds_read_b64_tr_b16 v[6:7], v168 offset:29696
	ds_read_b64_tr_b16 v[8:9], v168 offset:30208
	v_add_f32_e32 v10, v94, v10
	v_add_f32_e32 v10, v95, v10
	v_add_f32_e32 v10, v64, v10
	v_add_f32_e32 v80, v65, v10
	v_cvt_pk_bf16_f32 v154, v92, v93
	v_cvt_pk_bf16_f32 v155, v94, v95
	s_waitcnt lgkmcnt(12)
	v_mfma_f32_32x32x16_bf16 v[96:111], v[192:195], v[136:139], v[96:111]
	ds_read_b64_tr_b16 v[10:11], v168 offset:26624
	ds_read_b64_tr_b16 v[12:13], v168 offset:27136
	v_add_f32_e32 v80, v66, v80
	v_add_f32_e32 v80, v67, v80
	v_add_f32_e32 v80, v68, v80
	v_add_f32_e32 v80, v69, v80
	v_cvt_pk_bf16_f32 v148, v64, v65
	v_cvt_pk_bf16_f32 v149, v66, v67
	s_waitcnt lgkmcnt(13)
	v_mfma_f32_32x32x16_bf16 v[112:127], v[188:191], v[132:135], v[112:127]
	ds_read_b64_tr_b16 v[192:193], v168 offset:30720
	ds_read_b64_tr_b16 v[194:195], v168 offset:31232
	v_add_f32_e32 v64, v70, v80
	v_add_f32_e32 v64, v71, v64
	v_add_f32_e32 v64, v72, v64
	v_add_f32_e32 v64, v73, v64
	v_cvt_pk_bf16_f32 v150, v68, v69
	v_cvt_pk_bf16_f32 v151, v70, v71
	s_waitcnt lgkmcnt(14)
	v_mfma_f32_32x32x16_bf16 v[96:111], v[184:187], v[132:135], v[96:111]
	ds_read_b64_tr_b16 v[196:197], v168 offset:27648
	ds_read_b64_tr_b16 v[198:199], v168 offset:28160
	v_add_f32_e32 v64, v74, v64
	v_add_f32_e32 v64, v75, v64
	v_add_f32_e32 v64, v76, v64
	v_add_f32_e32 v64, v77, v64
	v_cvt_pk_bf16_f32 v144, v72, v73
	v_cvt_pk_bf16_f32 v145, v74, v75
	s_waitcnt lgkmcnt(14)
	v_mfma_f32_32x32x16_bf16 v[112:127], v[180:183], v[128:131], v[112:127]
	ds_read_b64_tr_b16 v[200:201], v168 offset:31744
	ds_read_b64_tr_b16 v[202:203], v168 offset:32256
	v_add_f32_e32 v64, v78, v64
	v_add_f32_e32 v64, v79, v64
	v_add_f32_e32 v168, 0, v64
	v_cvt_pk_bf16_f32 v146, v76, v77
	v_cvt_pk_bf16_f32 v147, v78, v79
	v_mfma_f32_32x32x16_bf16 v[96:111], v[176:179], v[128:131], v[96:111]
	v_lshl_add_u64 v[14:15], v[14:15], 0, s[66:67]
	s_add_i32 s1, s81, s62
	s_mov_b32 s6, m0
	s_mov_b32 m0, s1
	s_nop 0
	global_load_lds_dwordx4 v[14:15], off
	s_mov_b32 m0, s6
	v_lshl_add_u64 v[14:15], v[220:221], 0, s[86:87]
	s_add_i32 s1, s63, s97
	s_mov_b32 s6, m0
	s_mov_b32 m0, s1
	s_nop 0
	global_load_lds_dwordx4 v[14:15], off
	s_mov_b32 m0, s6
	ds_read_b128 v[64:67], v252 offset:256
	ds_read_b128 v[68:71], v252 offset:288
	ds_read_b128 v[72:75], v252 offset:320
	ds_read_b128 v[76:79], v252 offset:352
	ds_read_b128 v[170:173], v252 offset:384
	ds_read_b128 v[174:177], v252 offset:416
	ds_read_b128 v[178:181], v252 offset:448
	ds_read_b128 v[182:185], v252 offset:480
	s_add_i32 s80, s80, -3
	s_waitcnt lgkmcnt(4)
	v_add_f32_e32 v92, v124, v76
	v_add_f32_e32 v93, v125, v77
	v_add_f32_e32 v88, v120, v72
	v_add_f32_e32 v89, v121, v73
	v_add_f32_e32 v84, v116, v68
	v_add_f32_e32 v85, v117, v69
	v_add_f32_e32 v94, v126, v78
	v_add_f32_e32 v95, v127, v79
	v_add_f32_e32 v90, v122, v74
	v_add_f32_e32 v91, v123, v75
	v_add_f32_e32 v86, v118, v70
	v_add_f32_e32 v87, v119, v71
	v_add_f32_e32 v82, v114, v66
	v_add_f32_e32 v83, v115, v67
	v_add_f32_e32 v80, v112, v64
	v_add_f32_e32 v81, v113, v65
	s_waitcnt lgkmcnt(0)
	v_add_f32_e32 v76, v108, v182
	v_add_f32_e32 v77, v109, v183
	v_add_f32_e32 v72, v104, v178
	v_add_f32_e32 v73, v105, v179
	v_add_f32_e32 v68, v100, v174
	v_add_f32_e32 v69, v101, v175
	v_add_f32_e32 v78, v110, v184
	v_add_f32_e32 v79, v111, v185
	v_add_f32_e32 v74, v106, v180
	v_add_f32_e32 v75, v107, v181
	v_add_f32_e32 v70, v102, v176
	v_add_f32_e32 v71, v103, v177
	v_add_f32_e32 v66, v98, v172
	v_add_f32_e32 v67, v99, v173
	s_cmp_lt_i32 s80, -5
	v_add_f32_e32 v64, v96, v170
	v_add_f32_e32 v65, v97, v171
	s_cbranch_scc1 .LBB0_766
; __device__ __forceinline__ void cmask(f32x16&p0,f32x16&p1,int jb,int qrel,int hi){
;   const float NEG=-INFINITY; int kb=64*jb+4*hi;
;   #pragma unroll
;   for(int r=0;r<16;++r){int kv=kb+(r&3)+8*(r>>2); if(kv>qrel)p0[r]=NEG; if(kv+32>qrel)p1[r]=NEG;}
; }
	v_subrev_u32_e32 v15, 27, v251
	v_subrev_u32_e32 v14, 59, v251
	v_cmp_le_i32_e64 s[6:7], v15, v246
	v_cmp_le_i32_e32 vcc, v14, v246
	v_cmp_gt_i32_e64 s[38:39], v251, v246
	v_cndmask_b32_e64 v64, v238, v64, s[6:7]
	v_cmp_lt_i32_e64 s[6:7], v14, v246
	v_subrev_u32_e32 v14, 26, v251
	v_cmp_le_i32_e64 s[8:9], v14, v246
	v_subrev_u32_e32 v14, 57, v251
	s_nop 0
	v_cndmask_b32_e64 v65, v238, v65, s[8:9]
	v_cmp_le_i32_e64 s[8:9], v14, v246
	v_subrev_u32_e32 v14, 25, v251
	v_cmp_le_i32_e64 s[10:11], v14, v246
	v_subrev_u32_e32 v14, 56, v251
	s_nop 0
	v_cndmask_b32_e64 v66, v238, v66, s[10:11]
	v_cmp_le_i32_e64 s[10:11], v14, v246
	v_subrev_u32_e32 v14, 24, v251
	v_cmp_le_i32_e64 s[12:13], v14, v246
	v_subrev_u32_e32 v14, 51, v251
	s_nop 0
	v_cndmask_b32_e64 v67, v238, v67, s[12:13]
	v_cmp_le_i32_e64 s[12:13], v14, v246
	v_subrev_u32_e32 v14, 19, v251
	v_cmp_le_i32_e64 s[14:15], v14, v246
	v_subrev_u32_e32 v14, 50, v251
	s_nop 0
	v_cndmask_b32_e64 v68, v238, v68, s[14:15]
	v_cmp_le_i32_e64 s[14:15], v14, v246
	v_subrev_u32_e32 v14, 18, v251
	v_cmp_le_i32_e64 s[16:17], v14, v246
	v_subrev_u32_e32 v14, 49, v251
	s_nop 0
	v_cndmask_b32_e64 v69, v238, v69, s[16:17]
	v_cmp_le_i32_e64 s[16:17], v14, v246
	v_subrev_u32_e32 v14, 17, v251
	v_cmp_le_i32_e64 s[18:19], v14, v246
	v_subrev_u32_e32 v14, 48, v251
	s_nop 0
	v_cndmask_b32_e64 v70, v238, v70, s[18:19]
	v_cmp_le_i32_e64 s[18:19], v14, v246
	v_add_u32_e32 v14, -16, v251
	v_cmp_le_i32_e64 s[20:21], v14, v246
	v_subrev_u32_e32 v14, 43, v251
	s_nop 0
	v_cndmask_b32_e64 v71, v238, v71, s[20:21]
	v_cmp_le_i32_e64 s[20:21], v14, v246
	v_add_u32_e32 v14, -11, v251
	v_cmp_le_i32_e64 s[22:23], v14, v246
	v_subrev_u32_e32 v14, 42, v251
	s_nop 0
	v_cndmask_b32_e64 v72, v238, v72, s[22:23]
	v_cmp_le_i32_e64 s[22:23], v14, v246
	v_add_u32_e32 v14, -10, v251
	v_cmp_le_i32_e64 s[24:25], v14, v246
	v_subrev_u32_e32 v14, 41, v251
	s_nop 0
	v_cndmask_b32_e64 v73, v238, v73, s[24:25]
	v_cmp_le_i32_e64 s[24:25], v14, v246
	v_add_u32_e32 v14, -9, v251
	v_cmp_le_i32_e64 s[26:27], v14, v246
	v_subrev_u32_e32 v14, 40, v251
	s_nop 0
	v_cndmask_b32_e64 v74, v238, v74, s[26:27]
	v_cmp_le_i32_e64 s[26:27], v14, v246
	v_add_u32_e32 v14, -8, v251
	v_cmp_le_i32_e64 s[28:29], v14, v246
	v_subrev_u32_e32 v14, 35, v251
	s_nop 0
	v_cndmask_b32_e64 v75, v238, v75, s[28:29]
	v_cmp_le_i32_e64 s[28:29], v14, v246
	v_add_u32_e32 v14, -3, v251
	v_cmp_le_i32_e64 s[30:31], v14, v246
	v_subrev_u32_e32 v14, 34, v251
	s_nop 0
	v_cndmask_b32_e64 v76, v238, v76, s[30:31]
	v_cmp_le_i32_e64 s[30:31], v14, v246
	v_add_u32_e32 v14, -2, v251
	v_cmp_le_i32_e64 s[34:35], v14, v246
	v_subrev_u32_e32 v14, 33, v251
	s_nop 0
	v_cndmask_b32_e64 v77, v238, v77, s[34:35]
	v_cmp_le_i32_e64 s[34:35], v14, v246
	v_add_u32_e32 v14, -1, v251
	v_cmp_le_i32_e64 s[36:37], v14, v246
	v_subrev_u32_e32 v14, 32, v251
	s_nop 0
	v_cndmask_b32_e64 v78, v238, v78, s[36:37]
	v_cmp_le_i32_e64 s[36:37], v14, v246
	s_and_saveexec_b64 s[44:45], s[38:39]
	v_mov_b32_e32 v79, s73
	s_or_b64 exec, exec, s[44:45]
	v_cndmask_b32_e64 v81, v238, v81, s[6:7]
	v_cndmask_b32_e32 v80, v238, v80, vcc
	v_cndmask_b32_e64 v82, v238, v82, s[8:9]
	v_cndmask_b32_e64 v83, v238, v83, s[10:11]
	v_cndmask_b32_e64 v84, v238, v84, s[12:13]
	v_cndmask_b32_e64 v85, v238, v85, s[14:15]
	v_cndmask_b32_e64 v86, v238, v86, s[16:17]
	v_cndmask_b32_e64 v87, v238, v87, s[18:19]
	v_cndmask_b32_e64 v88, v238, v88, s[20:21]
	v_cndmask_b32_e64 v89, v238, v89, s[22:23]
	v_cndmask_b32_e64 v90, v238, v90, s[24:25]
	v_cndmask_b32_e64 v91, v238, v91, s[26:27]
	v_cndmask_b32_e64 v92, v238, v92, s[28:29]
	v_cndmask_b32_e64 v93, v238, v93, s[30:31]
	v_cndmask_b32_e64 v94, v238, v94, s[34:35]
	v_cndmask_b32_e64 v95, v238, v95, s[36:37]

; __device__ __forceinline__ void cmask(f32x16&p0,f32x16&p1,int jb,int qrel,int hi){
;   const float NEG=-INFINITY; int kb=64*jb+4*hi;
;   #pragma unroll
;   for(int r=0;r<16;++r){int kv=kb+(r&3)+8*(r>>2); if(kv>qrel)p0[r]=NEG; if(kv+32>qrel)p1[r]=NEG;}
; }
; template<int MODE> __device__ __forceinline__ void hook(f32x16&p0,f32x16&p1,int t,int NT,int qrel,int hi,lds_fptr tab,int dbase,int ibase){
;   if(MODE==0){
;     const lds_fptr tb=tab+64*t+4*hi;
;     #pragma unroll
;     for(int g=0;g<4;++g){ const f32x4a a=*(const __attribute__((address_space(3))) f32x4a*)(tb+8*g); const f32x4a c=*(const __attribute__((address_space(3))) f32x4a*)(tb+32+8*g);
;       p0[4*g+0]+=a.x;p0[4*g+1]+=a.y;p0[4*g+2]+=a.z;p0[4*g+3]+=a.w; p1[4*g+0]+=c.x;p1[4*g+1]+=c.y;p1[4*g+2]+=c.z;p1[4*g+3]+=c.w; }
;     const int jb=t-(NT-4); if(jb>=0)cmask(p0,p1,jb,qrel,hi);
.LBB0_782:
	s_add_i32 s6, s80, s97
	s_mov_b32 s7, m0
	s_mov_b32 m0, s6
	s_nop 0
	global_load_lds_dwordx4 v[220:221], off
	s_mov_b32 m0, s7
	ds_read_b128 v[64:67], v0
	ds_read_b128 v[68:71], v0 offset:32
	ds_read_b128 v[72:75], v0 offset:64
	ds_read_b128 v[76:79], v0 offset:96
	ds_read_b128 v[162:165], v0 offset:128
	ds_read_b128 v[166:169], v0 offset:160
	ds_read_b128 v[170:173], v0 offset:192
	ds_read_b128 v[174:177], v0 offset:224
	s_add_i32 s68, s45, s44
	s_waitcnt lgkmcnt(4)
	v_add_f32_e32 v94, v126, v78
	v_add_f32_e32 v95, v127, v79
	v_add_f32_e32 v90, v122, v74
	v_add_f32_e32 v91, v123, v75
	v_add_f32_e32 v86, v118, v70
	v_add_f32_e32 v87, v119, v71
	v_add_f32_e32 v82, v114, v66
	v_add_f32_e32 v83, v115, v67
	v_add_f32_e32 v92, v124, v76
	v_add_f32_e32 v93, v125, v77
	v_add_f32_e32 v88, v120, v72
	v_add_f32_e32 v89, v121, v73
	v_add_f32_e32 v84, v116, v68
	v_add_f32_e32 v85, v117, v69
	v_add_f32_e32 v80, v112, v64
	v_add_f32_e32 v81, v113, v65
	s_waitcnt lgkmcnt(0)
	v_add_f32_e32 v78, v110, v176
	v_add_f32_e32 v79, v111, v177
	v_add_f32_e32 v74, v106, v172
	v_add_f32_e32 v75, v107, v173
	v_add_f32_e32 v70, v102, v168
	v_add_f32_e32 v71, v103, v169
	v_add_f32_e32 v66, v98, v164
	v_add_f32_e32 v67, v99, v165
	v_add_f32_e32 v76, v108, v174
	v_add_f32_e32 v77, v109, v175
	v_add_f32_e32 v72, v104, v170
	v_add_f32_e32 v73, v105, v171
	v_add_f32_e32 v68, v100, v166
	v_add_f32_e32 v69, v101, v167
	s_cmp_lt_i32 s68, 0
	v_add_f32_e32 v64, v96, v162
	v_add_f32_e32 v65, v97, v163
	s_cbranch_scc1 .LBB0_786
	v_add_u32_e32 v96, s94, v242
	v_add_u32_e32 v97, 32, v96
	v_cmp_le_i32_e64 s[6:7], v97, v246
	v_add_u32_e32 v97, 33, v96
	v_cmp_le_i32_e64 s[8:9], v97, v246
	v_add_u32_e32 v97, 2, v96
	v_cmp_le_i32_e32 vcc, v96, v246
	v_cndmask_b32_e64 v65, v238, v65, s[8:9]
	v_cmp_le_i32_e64 s[8:9], v97, v246
	v_add_u32_e32 v97, 34, v96
	v_cmp_le_i32_e64 s[10:11], v97, v246
	v_add_u32_e32 v97, 3, v96
	v_cndmask_b32_e64 v64, v238, v64, s[6:7]
	v_cndmask_b32_e64 v66, v238, v66, s[10:11]
	v_cmp_le_i32_e64 s[10:11], v97, v246
	v_add_u32_e32 v97, 35, v96
	v_cmp_le_i32_e64 s[12:13], v97, v246
	v_add_u32_e32 v97, 8, v96
	v_cmp_lt_i32_e64 s[6:7], v96, v246
	v_cndmask_b32_e64 v67, v238, v67, s[12:13]
	v_cmp_le_i32_e64 s[12:13], v97, v246
	v_add_u32_e32 v97, 40, v96
	v_cmp_le_i32_e64 s[14:15], v97, v246
	v_add_u32_e32 v97, 9, v96
	s_nop 0
	v_cndmask_b32_e64 v68, v238, v68, s[14:15]
	v_cmp_le_i32_e64 s[14:15], v97, v246
	v_add_u32_e32 v97, 41, v96
	v_cmp_le_i32_e64 s[16:17], v97, v246
	v_add_u32_e32 v97, 10, v96
	s_nop 0
	v_cndmask_b32_e64 v69, v238, v69, s[16:17]
	v_cmp_le_i32_e64 s[16:17], v97, v246
	v_add_u32_e32 v97, 42, v96
	v_cmp_le_i32_e64 s[18:19], v97, v246
	v_add_u32_e32 v97, 11, v96
	s_nop 0
	v_cndmask_b32_e64 v70, v238, v70, s[18:19]
	v_cmp_le_i32_e64 s[18:19], v97, v246
	v_add_u32_e32 v97, 43, v96
	v_cmp_le_i32_e64 s[20:21], v97, v246
	v_add_u32_e32 v97, 16, v96
	s_nop 0
	v_cndmask_b32_e64 v71, v238, v71, s[20:21]
	v_cmp_le_i32_e64 s[20:21], v97, v246
	v_add_u32_e32 v97, 48, v96
	v_cmp_le_i32_e64 s[22:23], v97, v246
	v_add_u32_e32 v97, 17, v96
	s_nop 0
	v_cndmask_b32_e64 v72, v238, v72, s[22:23]
	v_cmp_le_i32_e64 s[22:23], v97, v246
	v_add_u32_e32 v97, 49, v96
	v_cmp_le_i32_e64 s[24:25], v97, v246
	v_add_u32_e32 v97, 18, v96
	s_nop 0
	v_cndmask_b32_e64 v73, v238, v73, s[24:25]
	v_cmp_le_i32_e64 s[24:25], v97, v246
	v_add_u32_e32 v97, 50, v96
	v_cmp_le_i32_e64 s[26:27], v97, v246
	v_add_u32_e32 v97, 19, v96
	s_nop 0
	v_cndmask_b32_e64 v74, v238, v74, s[26:27]
	v_cmp_le_i32_e64 s[26:27], v97, v246
	v_add_u32_e32 v97, 51, v96
	v_cmp_le_i32_e64 s[28:29], v97, v246
	v_add_u32_e32 v97, 24, v96
	s_nop 0
	v_cndmask_b32_e64 v75, v238, v75, s[28:29]
	v_cmp_le_i32_e64 s[28:29], v97, v246
	v_add_u32_e32 v97, 56, v96
	v_cmp_le_i32_e64 s[30:31], v97, v246
	v_add_u32_e32 v97, 25, v96
	s_nop 0
	v_cndmask_b32_e64 v76, v238, v76, s[30:31]
	v_cmp_le_i32_e64 s[30:31], v97, v246
	v_add_u32_e32 v97, 57, v96
	v_cmp_le_i32_e64 s[34:35], v97, v246
	v_add_u32_e32 v97, 26, v96
	s_nop 0
	v_cndmask_b32_e64 v77, v238, v77, s[34:35]
	v_cmp_le_i32_e64 s[34:35], v97, v246
	v_add_u32_e32 v97, 58, v96
	v_cmp_le_i32_e64 s[36:37], v97, v246
	v_add_u32_e32 v97, 27, v96
	v_add_u32_e32 v96, 59, v96
	v_cndmask_b32_e64 v78, v238, v78, s[36:37]
	v_cmp_le_i32_e64 s[36:37], v97, v246
	v_cmp_gt_i32_e64 s[38:39], v96, v246
	s_and_saveexec_b64 s[56:57], s[38:39]
	v_mov_b32_e32 v79, s73
	s_or_b64 exec, exec, s[56:57]
	v_cndmask_b32_e64 v81, v238, v81, s[6:7]
	v_cndmask_b32_e32 v80, v238, v80, vcc
	v_cndmask_b32_e64 v82, v238, v82, s[8:9]
	v_cndmask_b32_e64 v83, v238, v83, s[10:11]
	v_cndmask_b32_e64 v84, v238, v84, s[12:13]
	v_cndmask_b32_e64 v85, v238, v85, s[14:15]
	v_cndmask_b32_e64 v86, v238, v86, s[16:17]
	v_cndmask_b32_e64 v87, v238, v87, s[18:19]
	v_cndmask_b32_e64 v88, v238, v88, s[20:21]
	v_cndmask_b32_e64 v89, v238, v89, s[22:23]
	v_cndmask_b32_e64 v90, v238, v90, s[24:25]
	v_cndmask_b32_e64 v91, v238, v91, s[26:27]
	v_cndmask_b32_e64 v92, v238, v92, s[28:29]
	v_cndmask_b32_e64 v93, v238, v93, s[30:31]
	v_cndmask_b32_e64 v94, v238, v94, s[34:35]
	v_cndmask_b32_e64 v95, v238, v95, s[36:37]

; __device__ __forceinline__ void cmask(f32x16&p0,f32x16&p1,int jb,int qrel,int hi){
;   const float NEG=-INFINITY; int kb=64*jb+4*hi;
;   #pragma unroll
;   for(int r=0;r<16;++r){int kv=kb+(r&3)+8*(r>>2); if(kv>qrel)p0[r]=NEG; if(kv+32>qrel)p1[r]=NEG;}
; }
; template<int MODE> __device__ __forceinline__ void hook(f32x16&p0,f32x16&p1,int t,int NT,int qrel,int hi,lds_fptr tab,int dbase,int ibase){
;   if(MODE==0){
;     const lds_fptr tb=tab+64*t+4*hi;
;     #pragma unroll
;     for(int g=0;g<4;++g){ const f32x4a a=*(const __attribute__((address_space(3))) f32x4a*)(tb+8*g); const f32x4a c=*(const __attribute__((address_space(3))) f32x4a*)(tb+32+8*g);
;       p0[4*g+0]+=a.x;p0[4*g+1]+=a.y;p0[4*g+2]+=a.z;p0[4*g+3]+=a.w; p1[4*g+0]+=c.x;p1[4*g+1]+=c.y;p1[4*g+2]+=c.z;p1[4*g+3]+=c.w; }
;     const int jb=t-(NT-4); if(jb>=0)cmask(p0,p1,jb,qrel,hi);
.LBB0_799:
	ds_read_b128 v[64:67], v0 offset:256
	ds_read_b128 v[68:71], v0 offset:288
	ds_read_b128 v[72:75], v0 offset:320
	ds_read_b128 v[76:79], v0 offset:352
	ds_read_b128 v[228:231], v0 offset:384
	ds_read_b128 v[212:215], v0 offset:416
	ds_read_b128 v[234:237], v0 offset:448
	ds_read_b128 v[224:227], v0 offset:480
	s_add_i32 s68, s68, -4
	s_waitcnt lgkmcnt(4)
	v_add_f32_e32 v94, v126, v78
	v_add_f32_e32 v95, v127, v79
	v_add_f32_e32 v90, v122, v74
	v_add_f32_e32 v91, v123, v75
	v_add_f32_e32 v86, v118, v70
	v_add_f32_e32 v87, v119, v71
	v_add_f32_e32 v82, v114, v66
	v_add_f32_e32 v83, v115, v67
	v_add_f32_e32 v92, v124, v76
	v_add_f32_e32 v93, v125, v77
	v_add_f32_e32 v88, v120, v72
	v_add_f32_e32 v89, v121, v73
	v_add_f32_e32 v84, v116, v68
	v_add_f32_e32 v85, v117, v69
	v_add_f32_e32 v80, v112, v64
	v_add_f32_e32 v81, v113, v65
	s_waitcnt lgkmcnt(0)
	v_add_f32_e32 v78, v110, v226
	v_add_f32_e32 v79, v111, v227
	v_add_f32_e32 v74, v106, v236
	v_add_f32_e32 v75, v107, v237
	v_add_f32_e32 v70, v102, v214
	v_add_f32_e32 v71, v103, v215
	v_add_f32_e32 v66, v98, v230
	v_add_f32_e32 v67, v99, v231
	v_add_f32_e32 v76, v108, v224
	v_add_f32_e32 v77, v109, v225
	v_add_f32_e32 v72, v104, v234
	v_add_f32_e32 v73, v105, v235
	v_add_f32_e32 v68, v100, v212
	v_add_f32_e32 v69, v101, v213
	s_cmp_lt_i32 s68, -5
	v_add_f32_e32 v64, v96, v228
	v_add_f32_e32 v65, v97, v229
	s_cbranch_scc1 .LBB0_803
	v_add_u32_e32 v96, s41, v242
	v_add_u32_e32 v98, 0x60, v96
	v_add_u32_e32 v97, 64, v96
	v_cmp_le_i32_e64 s[6:7], v98, v246
	v_cmp_le_i32_e32 vcc, v97, v246
	s_nop 0
	v_cndmask_b32_e64 v64, v238, v64, s[6:7]
	v_cmp_lt_i32_e64 s[6:7], v97, v246
	v_add_u32_e32 v97, 0x61, v96
	v_cmp_le_i32_e64 s[8:9], v97, v246
	v_add_u32_e32 v97, 0x42, v96
	s_nop 0
	v_cndmask_b32_e64 v65, v238, v65, s[8:9]
	v_cmp_le_i32_e64 s[8:9], v97, v246
	v_add_u32_e32 v97, 0x62, v96
	v_cmp_le_i32_e64 s[10:11], v97, v246
	v_add_u32_e32 v97, 0x43, v96
	s_nop 0
	v_cndmask_b32_e64 v66, v238, v66, s[10:11]
	v_cmp_le_i32_e64 s[10:11], v97, v246
	v_add_u32_e32 v97, 0x63, v96
	v_cmp_le_i32_e64 s[12:13], v97, v246
	v_add_u32_e32 v97, 0x48, v96
	s_nop 0
	v_cndmask_b32_e64 v67, v238, v67, s[12:13]
	v_cmp_le_i32_e64 s[12:13], v97, v246
	v_add_u32_e32 v97, 0x68, v96
	v_cmp_le_i32_e64 s[14:15], v97, v246
	v_add_u32_e32 v97, 0x49, v96
	s_nop 0
	v_cndmask_b32_e64 v68, v238, v68, s[14:15]
	v_cmp_le_i32_e64 s[14:15], v97, v246
	v_add_u32_e32 v97, 0x69, v96
	v_cmp_le_i32_e64 s[16:17], v97, v246
	v_add_u32_e32 v97, 0x4a, v96
	s_nop 0
	v_cndmask_b32_e64 v69, v238, v69, s[16:17]
	v_cmp_le_i32_e64 s[16:17], v97, v246
	v_add_u32_e32 v97, 0x6a, v96
	v_cmp_le_i32_e64 s[18:19], v97, v246
	v_add_u32_e32 v97, 0x4b, v96
	s_nop 0
	v_cndmask_b32_e64 v70, v238, v70, s[18:19]
	v_cmp_le_i32_e64 s[18:19], v97, v246
	v_add_u32_e32 v97, 0x6b, v96
	v_cmp_le_i32_e64 s[20:21], v97, v246
	v_add_u32_e32 v97, 0x50, v96
	s_nop 0
	v_cndmask_b32_e64 v71, v238, v71, s[20:21]
	v_cmp_le_i32_e64 s[20:21], v97, v246
	v_add_u32_e32 v97, 0x70, v96
	v_cmp_le_i32_e64 s[22:23], v97, v246
	v_add_u32_e32 v97, 0x51, v96
	s_nop 0
	v_cndmask_b32_e64 v72, v238, v72, s[22:23]
	v_cmp_le_i32_e64 s[22:23], v97, v246
	v_add_u32_e32 v97, 0x71, v96
	v_cmp_le_i32_e64 s[24:25], v97, v246
	v_add_u32_e32 v97, 0x52, v96
	s_nop 0
	v_cndmask_b32_e64 v73, v238, v73, s[24:25]
	v_cmp_le_i32_e64 s[24:25], v97, v246
	v_add_u32_e32 v97, 0x72, v96
	v_cmp_le_i32_e64 s[26:27], v97, v246
	v_add_u32_e32 v97, 0x53, v96
	s_nop 0
	v_cndmask_b32_e64 v74, v238, v74, s[26:27]
	v_cmp_le_i32_e64 s[26:27], v97, v246
	v_add_u32_e32 v97, 0x73, v96
	v_cmp_le_i32_e64 s[28:29], v97, v246
	v_add_u32_e32 v97, 0x58, v96
	s_nop 0
	v_cndmask_b32_e64 v75, v238, v75, s[28:29]
	v_cmp_le_i32_e64 s[28:29], v97, v246
	v_add_u32_e32 v97, 0x78, v96
	v_cmp_le_i32_e64 s[30:31], v97, v246
	v_add_u32_e32 v97, 0x59, v96
	s_nop 0
	v_cndmask_b32_e64 v76, v238, v76, s[30:31]
	v_cmp_le_i32_e64 s[30:31], v97, v246
	v_add_u32_e32 v97, 0x79, v96
	v_cmp_le_i32_e64 s[34:35], v97, v246
	v_add_u32_e32 v97, 0x5a, v96
	s_nop 0
	v_cndmask_b32_e64 v77, v238, v77, s[34:35]
	v_cmp_le_i32_e64 s[34:35], v97, v246
	v_add_u32_e32 v97, 0x7a, v96
	v_cmp_le_i32_e64 s[36:37], v97, v246
	v_add_u32_e32 v97, 0x5b, v96
	v_add_u32_e32 v96, 0x7b, v96
	v_cndmask_b32_e64 v78, v238, v78, s[36:37]
	v_cmp_le_i32_e64 s[36:37], v97, v246
	v_cmp_gt_i32_e64 s[38:39], v96, v246
	s_and_saveexec_b64 s[68:69], s[38:39]
	v_mov_b32_e32 v79, s73
	s_or_b64 exec, exec, s[68:69]
	v_cndmask_b32_e64 v81, v238, v81, s[6:7]
	v_cndmask_b32_e32 v80, v238, v80, vcc
	v_cndmask_b32_e64 v82, v238, v82, s[8:9]
	v_cndmask_b32_e64 v83, v238, v83, s[10:11]
	v_cndmask_b32_e64 v84, v238, v84, s[12:13]
	v_cndmask_b32_e64 v85, v238, v85, s[14:15]
	v_cndmask_b32_e64 v86, v238, v86, s[16:17]
	v_cndmask_b32_e64 v87, v238, v87, s[18:19]
	v_cndmask_b32_e64 v88, v238, v88, s[20:21]
	v_cndmask_b32_e64 v89, v238, v89, s[22:23]
	v_cndmask_b32_e64 v90, v238, v90, s[24:25]
	v_cndmask_b32_e64 v91, v238, v91, s[26:27]
	v_cndmask_b32_e64 v92, v238, v92, s[28:29]
	v_cndmask_b32_e64 v93, v238, v93, s[30:31]
	v_cndmask_b32_e64 v94, v238, v94, s[34:35]
	v_cndmask_b32_e64 v95, v238, v95, s[36:37]

; template<int MODE> __device__ __forceinline__ void hook(f32x16&p0,f32x16&p1,int t,int NT,int qrel,int hi,lds_fptr tab,int dbase,int ibase){
;     ...
;     const lds_fptr tb=tab+64*t+4*hi;
;     #pragma unroll
;     for(int g=0;g<4;++g){ const f32x4a a=*(const __attribute__((address_space(3))) f32x4a*)(tb+8*g); const f32x4a c=*(const __attribute__((address_space(3))) f32x4a*)(tb+32+8*g);
;       p0[4*g+0]+=a.x;p0[4*g+1]+=a.y;p0[4*g+2]+=a.z;p0[4*g+3]+=a.w; p1[4*g+0]+=c.x;p1[4*g+1]+=c.y;p1[4*g+2]+=c.z;p1[4*g+3]+=c.w; }
;     const int jb=t-(NT-4); if(jb>=0)cmask(p0,p1,jb,qrel,hi);
.LBB0_833:
	v_add_u32_e32 v0, s80, v249
	ds_read_b64_tr_b16 v[6:7], v0 offset:24576
	ds_read_b64_tr_b16 v[8:9], v0 offset:25088
	v_add_f32_e32 v2, v80, v81
	v_add_f32_e32 v2, v82, v2
	v_add_f32_e32 v2, v83, v2
	v_add_f32_e32 v2, v84, v2
	v_add_f32_e32 v10, v85, v2
	v_cvt_pk_bf16_f32 v156, v80, v81
	v_cvt_pk_bf16_f32 v157, v82, v83
	s_waitcnt lgkmcnt(3)
	v_mfma_f32_32x32x16_bf16 v[96:111], v[188:191], v[140:143], v[48:63]
	ds_read_b64_tr_b16 v[2:3], v0 offset:28672
	ds_read_b64_tr_b16 v[4:5], v0 offset:29184
	s_waitcnt lgkmcnt(4)
	v_mfma_f32_32x32x16_bf16 v[48:63], v[184:187], v[140:143], v[48:63]
	v_add_f32_e32 v10, v86, v10
	v_add_f32_e32 v10, v87, v10
	v_add_f32_e32 v10, v88, v10
	v_add_f32_e32 v14, v89, v10
	v_cvt_pk_bf16_f32 v158, v84, v85
	v_cvt_pk_bf16_f32 v159, v86, v87
	ds_read_b64_tr_b16 v[10:11], v0 offset:25600
	ds_read_b64_tr_b16 v[12:13], v0 offset:26112
	v_add_f32_e32 v14, v90, v14
	v_add_f32_e32 v14, v91, v14
	v_add_f32_e32 v14, v92, v14
	v_add_f32_e32 v14, v93, v14
	v_cvt_pk_bf16_f32 v152, v88, v89
	v_cvt_pk_bf16_f32 v153, v90, v91
	v_mfma_f32_32x32x16_bf16 v[96:111], v[180:183], v[136:139], v[96:111]
	ds_read_b64_tr_b16 v[112:113], v0 offset:29696
	ds_read_b64_tr_b16 v[114:115], v0 offset:30208
	v_mfma_f32_32x32x16_bf16 v[48:63], v[176:179], v[136:139], v[48:63]
	v_add_f32_e32 v14, v94, v14
	v_add_f32_e32 v14, v95, v14
	v_add_f32_e32 v14, v64, v14
	v_add_f32_e32 v14, v65, v14
	v_cvt_pk_bf16_f32 v154, v92, v93
	v_cvt_pk_bf16_f32 v155, v94, v95
	ds_read_b64_tr_b16 v[116:117], v0 offset:26624
	ds_read_b64_tr_b16 v[118:119], v0 offset:27136
	v_add_f32_e32 v14, v66, v14
	v_add_f32_e32 v14, v67, v14
	v_add_f32_e32 v14, v68, v14
	v_add_f32_e32 v14, v69, v14
	v_cvt_pk_bf16_f32 v148, v64, v65
	v_cvt_pk_bf16_f32 v149, v66, v67
	v_mfma_f32_32x32x16_bf16 v[96:111], v[172:175], v[132:135], v[96:111]
	ds_read_b64_tr_b16 v[120:121], v0 offset:30720
	ds_read_b64_tr_b16 v[122:123], v0 offset:31232
	v_mfma_f32_32x32x16_bf16 v[48:63], v[168:171], v[132:135], v[48:63]
	v_add_f32_e32 v14, v70, v14
	v_add_f32_e32 v14, v71, v14
	v_add_f32_e32 v14, v72, v14
	v_add_f32_e32 v14, v73, v14
	v_cvt_pk_bf16_f32 v150, v68, v69
	v_cvt_pk_bf16_f32 v151, v70, v71
	ds_read_b64_tr_b16 v[124:125], v0 offset:27648
	ds_read_b64_tr_b16 v[126:127], v0 offset:28160
	v_add_f32_e32 v14, v74, v14
	v_add_f32_e32 v14, v75, v14
	v_add_f32_e32 v14, v76, v14
	v_add_f32_e32 v14, v77, v14
	v_cvt_pk_bf16_f32 v144, v72, v73
	v_cvt_pk_bf16_f32 v145, v74, v75
	v_mfma_f32_32x32x16_bf16 v[96:111], v[164:167], v[128:131], v[96:111]
	ds_read_b64_tr_b16 v[132:133], v0 offset:31744
	ds_read_b64_tr_b16 v[134:135], v0 offset:32256
	v_mfma_f32_32x32x16_bf16 v[48:63], v[160:163], v[128:131], v[48:63]
	v_add_f32_e32 v0, v78, v14
	v_add_f32_e32 v0, v79, v0
	v_add_f32_e32 v0, 0, v0
	v_cvt_pk_bf16_f32 v146, v76, v77
	v_cvt_pk_bf16_f32 v147, v78, v79
	s_lshl_b32 s1, s40, 8
	s_add_i32 s71, s71, s1
	v_add_u32_e32 v14, s71, v244
	v_add_u32_e32 v14, 0xffffff00, v14
	ds_read_b128 v[64:67], v14
	ds_read_b128 v[68:71], v14 offset:32
	ds_read_b128 v[72:75], v14 offset:128
	ds_read_b128 v[76:79], v14 offset:160
	ds_read_b128 v[80:83], v14 offset:64
	ds_read_b128 v[84:87], v14 offset:96
	ds_read_b128 v[88:91], v14 offset:192
	ds_read_b128 v[92:95], v14 offset:224
	s_waitcnt lgkmcnt(7)
	v_add_f32_e32 v14, v98, v66
	v_add_f32_e32 v15, v99, v67
	v_or_b32_e32 v67, 0xe0, v242
	s_waitcnt lgkmcnt(5)
	v_add_f32_e32 v48, v48, v72
	v_add_f32_e32 v49, v49, v73
	v_or_b32_e32 v66, 0xc0, v242
	v_cmp_le_i32_e32 vcc, v67, v246
	v_add_f32_e32 v64, v96, v64
	v_add_f32_e32 v65, v97, v65
	v_add_f32_e32 v50, v50, v74
	v_add_f32_e32 v51, v51, v75
	v_cndmask_b32_e32 v48, v238, v48, vcc
	v_cmp_lt_i32_e32 vcc, v66, v246
	v_add_f32_e32 v68, v100, v68
	v_add_f32_e32 v69, v101, v69
	s_waitcnt lgkmcnt(4)
	v_add_f32_e32 v52, v52, v76
	v_add_f32_e32 v53, v53, v77
	v_cndmask_b32_e32 v65, v238, v65, vcc
	v_cmp_le_i32_e32 vcc, v66, v246
	v_or_b32_e32 v66, 0xe1, v242
	v_add_f32_e32 v70, v102, v70
	v_add_f32_e32 v71, v103, v71
	v_cndmask_b32_e32 v64, v238, v64, vcc
	v_cmp_le_i32_e32 vcc, v66, v246
	v_or_b32_e32 v66, 0xc2, v242
	v_add_f32_e32 v54, v54, v78
	v_add_f32_e32 v55, v55, v79
	v_cndmask_b32_e32 v49, v238, v49, vcc
	v_cmp_le_i32_e32 vcc, v66, v246
	s_waitcnt lgkmcnt(3)
; __device__ __forceinline__ void cmask(f32x16&p0,f32x16&p1,int jb,int qrel,int hi){
;   const float NEG=-INFINITY; int kb=64*jb+4*hi;
;   #pragma unroll
;   for(int r=0;r<16;++r){int kv=kb+(r&3)+8*(r>>2); if(kv>qrel)p0[r]=NEG; if(kv+32>qrel)p1[r]=NEG;}
; }
	v_add_f32_e32 v80, v104, v80
	v_add_f32_e32 v81, v105, v81
	s_waitcnt lgkmcnt(1)
	v_add_f32_e32 v56, v56, v88
	v_add_f32_e32 v57, v57, v89
	v_cndmask_b32_e32 v66, v238, v14, vcc
	v_or_b32_e32 v14, 0xe2, v242
	v_cmp_le_i32_e32 vcc, v14, v246
	v_or_b32_e32 v14, 0xc3, v242
	v_add_f32_e32 v82, v106, v82
	v_add_f32_e32 v83, v107, v83
	v_cndmask_b32_e32 v50, v238, v50, vcc
	v_cmp_le_i32_e32 vcc, v14, v246
	v_or_b32_e32 v14, 0xe3, v242
	v_add_f32_e32 v58, v58, v90
	v_add_f32_e32 v59, v59, v91
	v_cndmask_b32_e32 v67, v238, v15, vcc
	v_cmp_le_i32_e32 vcc, v14, v246
	v_or_b32_e32 v14, 0xc8, v242
	v_add_f32_e32 v84, v108, v84
	v_add_f32_e32 v85, v109, v85
	v_cndmask_b32_e32 v51, v238, v51, vcc
	v_cmp_le_i32_e32 vcc, v14, v246
	v_or_b32_e32 v14, 0xe8, v242
	s_waitcnt lgkmcnt(0)
	v_add_f32_e32 v60, v60, v92
	v_add_f32_e32 v61, v61, v93
	v_cndmask_b32_e32 v68, v238, v68, vcc
	v_cmp_le_i32_e32 vcc, v14, v246
	v_or_b32_e32 v14, 0xc9, v242
	v_add_f32_e32 v86, v110, v86
	v_add_f32_e32 v87, v111, v87
	v_cndmask_b32_e32 v52, v238, v52, vcc
	v_cmp_le_i32_e32 vcc, v14, v246
	v_or_b32_e32 v14, 0xe9, v242
	v_add_f32_e32 v62, v62, v94
	v_add_f32_e32 v63, v63, v95
	v_cndmask_b32_e32 v69, v238, v69, vcc
	v_cmp_le_i32_e32 vcc, v14, v246
	v_or_b32_e32 v14, 0xca, v242
	v_max3_f32 v15, v66, v67, v49
	v_cndmask_b32_e32 v53, v238, v53, vcc
	v_cmp_le_i32_e32 vcc, v14, v246
	v_or_b32_e32 v14, 0xea, v242
	v_add_f32_e32 v0, v250, v0
	v_cndmask_b32_e32 v70, v238, v70, vcc
	v_cmp_le_i32_e32 vcc, v14, v246
	v_or_b32_e32 v14, 0xcb, v242
	s_nop 0
	v_cndmask_b32_e32 v54, v238, v54, vcc
	v_cmp_le_i32_e32 vcc, v14, v246
	v_or_b32_e32 v14, 0xeb, v242
	s_nop 0
	v_cndmask_b32_e32 v71, v238, v71, vcc
	v_cmp_le_i32_e32 vcc, v14, v246
	v_or_b32_e32 v14, 0xd0, v242
	v_max3_f32 v15, v15, v70, v71
	v_cndmask_b32_e32 v55, v238, v55, vcc
	v_cmp_le_i32_e32 vcc, v14, v246
	v_or_b32_e32 v14, 0xf0, v242
	v_max3_f32 v15, v15, v54, v55
	v_cndmask_b32_e32 v72, v238, v80, vcc
	v_cmp_le_i32_e32 vcc, v14, v246
	v_or_b32_e32 v14, 0xd1, v242
	s_nop 0
	v_cndmask_b32_e32 v56, v238, v56, vcc
	v_cmp_le_i32_e32 vcc, v14, v246
	v_or_b32_e32 v14, 0xf1, v242
	s_nop 0
	v_cndmask_b32_e32 v73, v238, v81, vcc
	v_cmp_le_i32_e32 vcc, v14, v246
	v_or_b32_e32 v14, 0xd2, v242
	s_nop 0
	v_cndmask_b32_e32 v57, v238, v57, vcc
	v_cmp_le_i32_e32 vcc, v14, v246
	v_or_b32_e32 v14, 0xf2, v242
	s_nop 0
	v_cndmask_b32_e32 v74, v238, v82, vcc
	v_cmp_le_i32_e32 vcc, v14, v246
	v_or_b32_e32 v14, 0xd3, v242
	s_nop 0
	v_cndmask_b32_e32 v58, v238, v58, vcc
	v_cmp_le_i32_e32 vcc, v14, v246
	v_or_b32_e32 v14, 0xf3, v242
	s_nop 0
	v_cndmask_b32_e32 v75, v238, v83, vcc
	v_cmp_le_i32_e32 vcc, v14, v246
	v_or_b32_e32 v14, 0xd8, v242
	v_max3_f32 v15, v15, v74, v75
	v_cndmask_b32_e32 v59, v238, v59, vcc
	v_cmp_le_i32_e32 vcc, v14, v246
	v_or_b32_e32 v14, 0xf8, v242
	v_max3_f32 v15, v15, v58, v59
	v_cndmask_b32_e32 v76, v238, v84, vcc
	v_cmp_le_i32_e32 vcc, v14, v246
	v_or_b32_e32 v14, 0xd9, v242
	s_nop 0
	v_cndmask_b32_e32 v60, v238, v60, vcc
	v_cmp_le_i32_e32 vcc, v14, v246
	v_or_b32_e32 v14, 0xf9, v242
	s_nop 0
	v_cndmask_b32_e32 v77, v238, v85, vcc
	v_cmp_le_i32_e32 vcc, v14, v246
	v_or_b32_e32 v14, 0xda, v242
	s_nop 0
	v_cndmask_b32_e32 v61, v238, v61, vcc
	v_cmp_le_i32_e32 vcc, v14, v246
	v_or_b32_e32 v14, 0xfa, v242
	s_nop 0
	v_cndmask_b32_e32 v78, v238, v86, vcc
	v_cmp_le_i32_e32 vcc, v14, v246
	v_or_b32_e32 v14, 0xdb, v242
	s_nop 0
	v_cndmask_b32_e32 v62, v238, v62, vcc
	v_cmp_le_i32_e32 vcc, v14, v246
	v_or_b32_e32 v14, 0xfb, v242
	s_nop 0
	v_cndmask_b32_e32 v79, v238, v87, vcc
	v_cmp_le_i32_e32 vcc, v14, v246
	v_max_f32_e32 v14, v64, v65
	v_max3_f32 v14, v14, v48, v50
	v_max3_f32 v14, v14, v51, v68
	v_max3_f32 v14, v14, v69, v52
	v_max3_f32 v14, v14, v53, v72
	v_max3_f32 v14, v14, v73, v56
	v_cndmask_b32_e32 v63, v238, v63, vcc
	v_max3_f32 v14, v14, v57, v76
	v_max3_f32 v15, v15, v78, v79
	v_max3_f32 v14, v14, v77, v60
	v_max3_f32 v15, v15, v62, v63
	v_max3_f32 v14, v14, v61, v15
	v_mov_b32_e32 v15, v14
	s_nop 1
	v_permlane32_swap_b32_e32 v14, v15
	v_max_f32_e32 v15, v15, v15
	v_max_f32_e32 v14, v14, v14
	v_max_f32_e32 v14, v14, v15
	v_cmp_lt_f32_e32 vcc, s77, v14
	s_cmp_lg_u64 vcc, 0
	s_cselect_b64 s[4:5], -1, 0
	s_cbranch_vccnz .LBB0_838

; #define WAIT_BAR(N) asm volatile("s_waitcnt vmcnt(" #N ") lgkmcnt(0)\n\ts_barrier":::"memory")
;   #define DMA_K(t,slot) glds16(ksrc+(long)(t)*KVBLK*DM,(unsigned)__builtin_amdgcn_readfirstlane(kdst+(slot)))
; template<int MODE,int THRL> __device__ __forceinline__ void attn_unit(int b,int h,int qb,const bf16*Q,const bf16*__restrict__ K,const bf16*__restrict__ V,bf16*O,char*shm,const float*aux0,const float*aux1,const float*aux2){
;     ...
;   const bf16*Kh=K+(rowbase+(long)T0*KVBLK)*DM+h*D,*Vh=V+(rowbase+(long)T0*KVBLK)*DM+h*D;
;   const unsigned lds0=(unsigned)(uintptr_t)shm;
;   float*wsf=(float*)(shm+LDS_WS)+wid*64;
;   const bf16*ksrc=Kh+(long)lane*DM+wid*8;
;   const bf16*vsrc=Vh+(long)(16*(wid&3)+(lane>>2))*DM+(wid>>2)*32+(lane&3)*8;
;   const unsigned kdst=lds0+LDS_K+wid*1024, vdst=lds0+LDS_V+wid*1024;
;     ...
;   const int vb0=(int)(lds0+LDS_V)+((lane>>4)&1)*32+(lane&3)*8+(4*hi+((lane&15)>>2))*64;
;   const char*Kbase=shm+LDS_K; bf16x8 kf[8];
;   const lds_cptr shm3=(lds_cptr)shm; const lds_cptr kp0=shm3+LDS_K+hi*1024+r32*16; const lds_cptr vp0=shm3+LDS_V+((lane>>4)&1)*32+(lane&3)*8+(4*hi+((lane&15)>>2))*64;
;   const int NT=(q0+QB)/KVBLK-T0;
;   const lds_fptr tab=(lds_fptr)(shm3+TAB_OFF);
;   const int dbase=4*qb+(wid>>1)-T0, ibase=32*(wid&1)+r32+128; const lds_fptr tabh=(MODE==0)?tab+64*T0:tab;
;   if(MODE==0){
;     const lds_fptr bp=tab+8192;
;     const int nkeys=q0+QB; const float*cum=aux0+(long)(b*NHEAD+h)*SEQ;
;     for(int j0=64*T0+tid;j0<nkeys;j0+=2048){ float cv[4];
;       #pragma unroll
;       for(int u4=0;u4<4;++u4){const int jj=j0+512*u4; cv[u4]=(jj<nkeys)?cum[jj]:0.f;}
;       #pragma unroll
;       for(int u4=0;u4<4;++u4){const int jj=j0+512*u4; if(jj<nkeys) tab[jj]=-(cv[u4]+bp[jj>>6])*LOG2E;} }
;   } else {
;     if(tid<257) tab[tid]=aux0[tid]*LOG2E;
;   }
;   DMA_K(0,0);DMA_V(0,0);DMA_K(1,SLOTB);
;   bf16x8 qr[4];
;   #pragma unroll
;   for(int d0=0;d0<4;++d0)qr[d0]=*reinterpret_cast<const bf16x8*>(&Qw[(long)r32*DM+d0*16+hi*8]);
;   float mhat=0.f,l_reg=0.f;f32x16 o[2];o[0]=f32x16{};o[1]=f32x16{};f32x16 negm=f32x16{};asm volatile("":"+v"(negm));
;   const int qrel=wid*QBLK+r32;
;     ...
;   bool resc=false;
;     ...
;   f32x16 pA0,pA1,pB0,pB1;
;   int sl_prev=0,sl_cur=0,sl_next=SLOTB;
;     ...
;   DMA_K(2,2*SLOTB);
;   WAIT_BAR(3);
;   qkt(pA0,pA1,Kbase,qr,negm,r32,hi);asm volatile("s_nop 15\n\ts_nop 7":"+v"(pA0),"+v"(pA1));CMASK(pA0,pA1,0);
.LBB0_845:
	s_or_b64 exec, exec, s[4:5]
	s_and_b64 s[4:5], s[6:7], exec
	s_cselect_b32 s1, s76, s83
	s_ashr_i32 s34, s14, 6
	s_lshl_b32 s17, s1, 8
	s_lshl_b32 s15, s34, 5
	s_or_b32 s4, s90, s17
	s_ashr_i32 s5, s15, 31
	s_add_u32 s4, s4, s15
	s_addc_u32 s5, s91, s5
	s_lshl_b64 s[4:5], s[4:5], 10
	s_add_u32 s12, s26, s4
	s_addc_u32 s13, s27, s5
	s_lshl_b32 s22, s1, 2
	s_add_i32 s4, s22, -8
	s_cmp_gt_u32 s1, 2
	s_cselect_b32 s94, s4, 0
	s_lshl_b64 s[4:5], s[94:95], 15
	s_add_u32 s4, s4, s8
	s_addc_u32 s5, s5, s9
	s_lshl_b64 s[4:5], s[4:5], 1
	s_add_u32 s18, s28, s4
	v_and_b32_e32 v217, 63, v34
	s_addc_u32 s19, s29, s5
	s_add_u32 s4, s30, s4
	v_lshlrev_b32_e32 v0, 10, v217
	s_addc_u32 s5, s31, s5
	v_lshl_add_u64 v[2:3], s[18:19], 0, v[0:1]
	s_lshl_b32 s1, s34, 4
	v_bfe_u32 v0, v34, 2, 4
	s_lshl_b32 s18, s34, 3
	v_and_or_b32 v0, s1, 48, v0
	s_ashr_i32 s19, s18, 31
	v_lshlrev_b32_e32 v0, 10, v0
	s_ashr_i32 s1, s14, 3
	v_lshl_add_u64 v[220:221], s[18:19], 1, v[2:3]
	v_lshl_add_u64 v[2:3], s[4:5], 0, v[0:1]
	s_and_b32 s4, s1, 0xffffffe0
	s_ashr_i32 s5, s4, 31
	s_lshl_b32 s1, s34, 10
	v_lshlrev_b32_e32 v241, 3, v34
	s_cmp_lg_u32 0, -1
	v_lshl_add_u64 v[2:3], s[4:5], 1, v[2:3]
	v_and_b32_e32 v244, 24, v241
	s_cselect_b32 s4, 0, 0
	v_and_b32_e32 v242, 31, v34
	v_lshlrev_b32_e32 v0, 1, v244
	s_add_i32 s37, s1, s4
	s_mov_b32 s4, m0
	s_mov_b32 m0, s37
	s_nop 0
	global_load_lds_dwordx4 v[220:221], off
	s_mov_b32 m0, s4
	v_bfe_u32 v243, v34, 5, 1
	v_lshl_add_u64 v[222:223], v[2:3], 0, v[0:1]
	s_add_i32 s38, s37, 0x6000
	s_mov_b32 s4, m0
	s_mov_b32 m0, s38
	s_nop 0
	global_load_lds_dwordx4 v[222:223], off
	s_mov_b32 m0, s4
	v_lshlrev_b32_e32 v0, 10, v242
	v_lshl_add_u64 v[2:3], v[220:221], 0, s[50:51]
	s_add_i32 s4, s37, 0x2000
	s_mov_b32 s5, m0
	s_mov_b32 m0, s4
	s_nop 0
	global_load_lds_dwordx4 v[2:3], off
	s_mov_b32 m0, s5
	v_lshl_or_b32 v0, v243, 4, v0
	global_load_dwordx4 v[148:151], v0, s[12:13]
	global_load_dwordx4 v[136:139], v0, s[12:13] offset:32
	global_load_dwordx4 v[132:135], v0, s[12:13] offset:64
	global_load_dwordx4 v[128:131], v0, s[12:13] offset:96
	v_mov_b32_e32 v2, v1
	v_mov_b32_e32 v3, v1
	v_mov_b32_e32 v4, v1
	v_mov_b32_e32 v5, v1
	v_mov_b32_e32 v6, v1
	v_mov_b32_e32 v7, v1
	v_mov_b32_e32 v8, v1
	v_mov_b32_e32 v9, v1
	v_mov_b32_e32 v10, v1
	v_mov_b32_e32 v11, v1
	v_mov_b32_e32 v12, v1
	v_mov_b32_e32 v13, v1
	v_mov_b32_e32 v14, v1
	v_mov_b32_e32 v15, v1
	v_lshlrev_b32_e32 v0, 10, v243
	v_lshlrev_b32_e32 v16, 4, v242
	v_add3_u32 v250, 0, v0, v16
	v_mov_b32_e32 v0, v1
	v_mov_b64_e32 v[16:17], v[14:15]
	v_mov_b64_e32 v[14:15], v[12:13]
	v_mov_b64_e32 v[12:13], v[10:11]
	v_mov_b64_e32 v[10:11], v[8:9]
	v_mov_b64_e32 v[8:9], v[6:7]
	v_mov_b64_e32 v[6:7], v[4:5]
	v_mov_b64_e32 v[4:5], v[2:3]
	v_mov_b64_e32 v[2:3], v[0:1]
	v_lshl_add_u64 v[18:19], v[220:221], 0, s[74:75]
	s_add_i32 s4, s37, 0x4000
	s_mov_b32 s5, m0
	s_mov_b32 m0, s4
	s_nop 0
	global_load_lds_dwordx4 v[18:19], off
	s_mov_b32 m0, s5
	s_waitcnt vmcnt(3) lgkmcnt(0)
	s_barrier
	ds_read_b128 v[36:39], v250
	ds_read_b128 v[40:43], v250 offset:512
	s_ashr_i32 s23, s14, 7
	s_sub_i32 s4, s22, s94
	s_and_b32 s24, s15, 32
	s_add_i32 s36, s23, s4
	v_or_b32_e32 v0, s24, v242
	v_or_b32_e32 v248, 0x80, v0
	s_cmp_lt_u32 s36, 9
	s_mov_b64 s[4:5], -1
	s_waitcnt vmcnt(3) lgkmcnt(1)
	v_mfma_f32_32x32x16_bf16 v[18:33], v[36:39], v[148:151], v[2:17]
	s_waitcnt lgkmcnt(0)
	v_mfma_f32_32x32x16_bf16 v[2:17], v[40:43], v[148:151], v[2:17]
	ds_read_b128 v[36:39], v250 offset:2048
	ds_read_b128 v[40:43], v250 offset:2560
	s_waitcnt vmcnt(2) lgkmcnt(1)
	v_mfma_f32_32x32x16_bf16 v[18:33], v[36:39], v[136:139], v[18:33]
	s_waitcnt lgkmcnt(0)
	v_mfma_f32_32x32x16_bf16 v[2:17], v[40:43], v[136:139], v[2:17]
	ds_read_b128 v[36:39], v250 offset:4096
	ds_read_b128 v[40:43], v250 offset:4608
	s_waitcnt vmcnt(1) lgkmcnt(1)
	v_mfma_f32_32x32x16_bf16 v[18:33], v[36:39], v[132:135], v[18:33]
	s_waitcnt lgkmcnt(0)
	v_mfma_f32_32x32x16_bf16 v[2:17], v[40:43], v[132:135], v[2:17]
	ds_read_b128 v[36:39], v250 offset:6144
	ds_read_b128 v[40:43], v250 offset:6656
	s_waitcnt vmcnt(0) lgkmcnt(1)
	v_mfma_f32_32x32x16_bf16 v[18:33], v[36:39], v[128:131], v[18:33]
	s_waitcnt lgkmcnt(0)
	v_mfma_f32_32x32x16_bf16 v[2:17], v[40:43], v[128:131], v[2:17]
	s_nop 15
	s_nop 7
	s_cbranch_scc0 .LBB0_851
	s_cmp_lt_u32 s36, 3
	s_cbranch_scc0 .LBB0_848
; template<int MODE> __device__ __forceinline__ void hook(f32x16&p0,f32x16&p1,int t,int NT,int qrel,int hi,lds_fptr tab,int dbase,int ibase){
;     ...
;     const int delta=dbase-t;
;     if(delta<0||delta>8){
;       #pragma unroll
;       for(int r=0;r<16;++r){p0[r]=NEGBIG;p1[r]=NEGBIG;}
;     } else if(delta>=3){ const float cf=tab[256];
;       #pragma unroll
;       for(int r=0;r<16;++r){p0[r]+=cf;p1[r]+=cf;}
;     } else { const int ib=64*delta+ibase-4*hi;
;       #pragma unroll
;       for(int r=0;r<16;++r){ const int kc=(r&3)+8*(r>>2); int i0=ib-kc, i1=ib-32-kc; i0=i0>256?256:i0; i1=i1>256?256:i1; p0[r]+=tab[i0]; p1[r]+=tab[i1]; }
;     }
	v_lshlrev_b32_e32 v0, 2, v243
	v_sub_u32_e32 v0, v248, v0
	v_lshl_add_u32 v0, s36, 6, v0
	v_min_u32_e32 v36, 0x120, v0
	s_add_i32 s4, 0, 0x15000
	v_min_u32_e32 v37, 0x101, v0
	v_min_u32_e32 v38, 0x121, v0
	v_min_u32_e32 v39, 0x102, v0
	v_min_u32_e32 v40, 0x122, v0
	v_min_u32_e32 v41, 0x103, v0
	v_min_u32_e32 v35, 0x100, v0
	v_lshl_add_u32 v36, v36, 2, s4
	v_lshlrev_b32_e32 v37, 2, v37
	v_lshl_add_u32 v38, v38, 2, s4
	v_lshlrev_b32_e32 v39, 2, v39
	v_lshl_add_u32 v40, v40, 2, s4
	v_min_u32_e32 v42, 0x123, v0
	v_lshlrev_b32_e32 v41, 2, v41
	v_lshl_add_u32 v35, v35, 2, s4
	v_add_u32_e32 v36, 0xffffff80, v36
	v_add3_u32 v37, s4, v37, -4
	v_add_u32_e32 v38, 0xffffff7c, v38
	v_add3_u32 v39, s4, v39, -8
	v_add_u32_e32 v40, 0xffffff78, v40
	v_add3_u32 v41, s4, v41, -12
	v_lshl_add_u32 v42, v42, 2, s4
	v_add_u32_e32 v42, 0xffffff74, v42
	ds_read_b32 v64, v35
	ds_read_b32 v36, v36
	ds_read_b32 v65, v37
	ds_read_b32 v37, v38
	ds_read_b32 v62, v39
	ds_read_b32 v38, v40
	ds_read_b32 v63, v41
	ds_read_b32 v39, v42
	v_min_u32_e32 v35, 0x108, v0
	v_min_u32_e32 v40, 0x128, v0
	v_min_u32_e32 v41, 0x109, v0
	v_min_u32_e32 v46, 0x12b, v0
	v_lshl_add_u32 v35, v35, 2, s4
	v_lshl_add_u32 v40, v40, 2, s4
	v_min_u32_e32 v42, 0x129, v0
	v_lshl_add_u32 v41, v41, 2, s4
	v_min_u32_e32 v43, 0x10a, v0
	v_min_u32_e32 v44, 0x12a, v0
	v_min_u32_e32 v45, 0x10b, v0
	v_lshl_add_u32 v46, v46, 2, s4
	v_subrev_u32_e32 v35, 32, v35
	v_add_u32_e32 v40, 0xffffff60, v40
	v_subrev_u32_e32 v41, 36, v41
	v_lshl_add_u32 v42, v42, 2, s4
	v_lshl_add_u32 v43, v43, 2, s4
	v_lshl_add_u32 v44, v44, 2, s4
	v_lshl_add_u32 v45, v45, 2, s4
	v_add_u32_e32 v47, 0xffffff54, v46
	v_add_u32_e32 v42, 0xffffff5c, v42
	v_subrev_u32_e32 v43, 40, v43
	v_add_u32_e32 v44, 0xffffff58, v44
	v_subrev_u32_e32 v45, 44, v45
	ds_read_b32 v60, v35
	ds_read_b32 v40, v40
	ds_read_b32 v61, v41
	ds_read_b32 v41, v42
	ds_read_b32 v58, v43
	ds_read_b32 v46, v44
	ds_read_b32 v59, v45
	ds_read_b32 v47, v47
	v_min_u32_e32 v48, 0x132, v0
	v_lshl_add_u32 v48, v48, 2, s4
	v_min_u32_e32 v35, 0x110, v0
	v_min_u32_e32 v42, 0x130, v0
	v_min_u32_e32 v43, 0x111, v0
	v_add_u32_e32 v50, 0xffffff38, v48
	v_min_u32_e32 v48, 0x113, v0
	v_lshl_add_u32 v35, v35, 2, s4
	v_lshl_add_u32 v42, v42, 2, s4
	v_min_u32_e32 v44, 0x131, v0
	v_lshl_add_u32 v43, v43, 2, s4
	v_min_u32_e32 v45, 0x112, v0
	v_min_u32_e32 v49, 0x133, v0
	v_lshl_add_u32 v48, v48, 2, s4
	v_subrev_u32_e32 v35, 64, v35
	v_add_u32_e32 v42, 0xffffff40, v42
	v_add_u32_e32 v43, 0xffffffbc, v43
	v_lshl_add_u32 v44, v44, 2, s4
	v_lshl_add_u32 v45, v45, 2, s4
	v_add_u32_e32 v51, 0xffffffb4, v48
	v_lshl_add_u32 v48, v49, 2, s4
	v_add_u32_e32 v44, 0xffffff3c, v44
	v_add_u32_e32 v45, 0xffffffb8, v45
	v_add_u32_e32 v52, 0xffffff34, v48
	ds_read_b32 v56, v35
	ds_read_b32 v48, v42
	ds_read_b32 v57, v43
	ds_read_b32 v49, v44
	ds_read_b32 v54, v45
	ds_read_b32 v50, v50
	ds_read_b32 v55, v51
	ds_read_b32 v51, v52
	s_waitcnt lgkmcnt(12)
	v_add_f32_e32 v42, v6, v40
	v_add_f32_e32 v43, v7, v41
	s_waitcnt lgkmcnt(8)
	v_add_f32_e32 v40, v8, v46
	v_add_f32_e32 v41, v9, v47
	v_min_u32_e32 v47, 0x119, v0
	v_add_f32_e32 v44, v4, v38
	v_add_f32_e32 v45, v5, v39
	s_waitcnt lgkmcnt(4)
	v_add_f32_e32 v38, v10, v48
	v_add_f32_e32 v39, v11, v49
	v_min_u32_e32 v48, 0x139, v0
	v_lshl_add_u32 v47, v47, 2, s4
	v_add_u32_e32 v49, 0xffffff9c, v47
	v_lshl_add_u32 v47, v48, 2, s4
	v_min_u32_e32 v48, 0x11a, v0
	v_min_u32_e32 v52, 0x13a, v0
	v_lshl_add_u32 v48, v48, 2, s4
	v_add_u32_e32 v53, 0xffffff98, v48
	v_lshl_add_u32 v48, v52, 2, s4
	v_min_u32_e32 v35, 0x118, v0
	v_min_u32_e32 v46, 0x138, v0
	v_add_u32_e32 v52, 0xffffff18, v48
	v_min_u32_e32 v48, 0x11b, v0
	v_lshl_add_u32 v35, v35, 2, s4
	v_lshl_add_u32 v46, v46, 2, s4
	v_min_u32_e32 v0, 0x13b, v0
	v_lshl_add_u32 v48, v48, 2, s4
	v_add_u32_e32 v35, 0xffffffa0, v35
	v_add_u32_e32 v46, 0xffffff20, v46
	v_add_u32_e32 v47, 0xffffff1c, v47
	v_add_u32_e32 v67, 0xffffff94, v48
	v_lshl_add_u32 v0, v0, 2, s4
	v_add_u32_e32 v0, 0xffffff14, v0
	ds_read_b32 v48, v35
	ds_read_b32 v46, v46
	ds_read_b32 v47, v47
	ds_read_b32 v66, v53
	ds_read_b32 v35, v52
	ds_read_b32 v67, v67
	ds_read_b32 v68, v0
	ds_read_b32 v49, v49
	v_add_f32_e32 v36, v2, v36
	v_add_f32_e32 v37, v3, v37
	s_waitcnt lgkmcnt(8)
	v_add_f32_e32 v52, v12, v50
	v_add_f32_e32 v53, v13, v51
	s_waitcnt lgkmcnt(5)
	v_add_f32_e32 v50, v14, v46
	v_add_f32_e32 v51, v15, v47
	s_waitcnt lgkmcnt(3)
	v_add_f32_e32 v0, v16, v35
	s_waitcnt lgkmcnt(2)
	v_add_f32_e32 v46, v32, v66
	v_add_f32_e32 v47, v33, v67
	s_waitcnt lgkmcnt(0)
	v_add_f32_e32 v48, v30, v48
	v_add_f32_e32 v49, v31, v49
	v_add_f32_e32 v54, v28, v54
	v_add_f32_e32 v55, v29, v55
	v_add_f32_e32 v56, v26, v56
	v_add_f32_e32 v57, v27, v57
	v_add_f32_e32 v58, v24, v58
	v_add_f32_e32 v59, v25, v59
	v_add_f32_e32 v60, v22, v60
	v_add_f32_e32 v61, v23, v61
	v_add_f32_e32 v62, v20, v62
	v_add_f32_e32 v63, v21, v63
	v_add_f32_e32 v64, v18, v64
	v_add_f32_e32 v65, v19, v65
	v_add_f32_e32 v35, v17, v68
	s_mov_b64 s[4:5], 0

.LBB0_855:
	v_add_u32_e32 v0, s18, v251
	ds_read_b64_tr_b16 v[192:193], v0 offset:24576
	ds_read_b64_tr_b16 v[194:195], v0 offset:25088
	s_waitcnt lgkmcnt(9)
	v_mfma_f32_32x32x16_bf16 v[96:111], v[188:191], v[148:151], v[48:63]
	v_add_f32_e32 v2, v80, v81
	v_add_f32_e32 v2, v82, v2
	v_add_f32_e32 v2, v83, v2
	v_add_f32_e32 v2, v84, v2
	v_add_f32_e32 v2, v85, v2
	v_cvt_pk_bf16_f32 v156, v80, v81
	v_cvt_pk_bf16_f32 v157, v82, v83
	ds_read_b64_tr_b16 v[188:189], v0 offset:28672
	ds_read_b64_tr_b16 v[190:191], v0 offset:29184
	s_waitcnt lgkmcnt(10)
	v_mfma_f32_32x32x16_bf16 v[112:127], v[184:187], v[148:151], v[48:63]
	v_add_f32_e32 v2, v86, v2
	v_add_f32_e32 v2, v87, v2
	v_add_f32_e32 v2, v88, v2
	v_add_f32_e32 v2, v89, v2
	v_cvt_pk_bf16_f32 v158, v84, v85
	v_cvt_pk_bf16_f32 v159, v86, v87
	ds_read_b64_tr_b16 v[10:11], v0 offset:25600
	ds_read_b64_tr_b16 v[12:13], v0 offset:26112
	s_waitcnt lgkmcnt(11)
	v_mfma_f32_32x32x16_bf16 v[96:111], v[180:183], v[136:139], v[96:111]
	v_add_f32_e32 v2, v90, v2
	v_add_f32_e32 v2, v91, v2
	v_add_f32_e32 v2, v92, v2
	v_add_f32_e32 v2, v93, v2
	v_cvt_pk_bf16_f32 v152, v88, v89
	v_cvt_pk_bf16_f32 v153, v90, v91
	ds_read_b64_tr_b16 v[180:181], v0 offset:29696
	ds_read_b64_tr_b16 v[182:183], v0 offset:30208
	s_waitcnt lgkmcnt(12)
	v_mfma_f32_32x32x16_bf16 v[112:127], v[176:179], v[136:139], v[112:127]
	v_add_f32_e32 v2, v94, v2
	v_add_f32_e32 v2, v95, v2
	v_add_f32_e32 v2, v64, v2
	v_add_f32_e32 v2, v65, v2
	v_cvt_pk_bf16_f32 v154, v92, v93
	v_cvt_pk_bf16_f32 v155, v94, v95
	ds_read_b64_tr_b16 v[176:177], v0 offset:26624
	ds_read_b64_tr_b16 v[178:179], v0 offset:27136
	s_waitcnt lgkmcnt(13)
	v_mfma_f32_32x32x16_bf16 v[96:111], v[172:175], v[132:135], v[96:111]
	v_add_f32_e32 v2, v66, v2
	v_add_f32_e32 v2, v67, v2
	v_add_f32_e32 v2, v68, v2
	v_add_f32_e32 v6, v69, v2
	v_cvt_pk_bf16_f32 v144, v64, v65
	v_cvt_pk_bf16_f32 v145, v66, v67
	ds_read_b64_tr_b16 v[2:3], v0 offset:30720
	ds_read_b64_tr_b16 v[4:5], v0 offset:31232
	s_waitcnt lgkmcnt(14)
	v_mfma_f32_32x32x16_bf16 v[112:127], v[168:171], v[132:135], v[112:127]
	v_add_f32_e32 v6, v70, v6
	v_add_f32_e32 v6, v71, v6
	v_add_f32_e32 v6, v72, v6
	v_add_f32_e32 v14, v73, v6
	v_cvt_pk_bf16_f32 v146, v68, v69
	v_cvt_pk_bf16_f32 v147, v70, v71
	ds_read_b64_tr_b16 v[6:7], v0 offset:27648
	ds_read_b64_tr_b16 v[8:9], v0 offset:28160
	s_waitcnt lgkmcnt(14)
	v_mfma_f32_32x32x16_bf16 v[96:111], v[164:167], v[128:131], v[96:111]
	v_add_f32_e32 v14, v74, v14
	v_add_f32_e32 v14, v75, v14
	v_add_f32_e32 v14, v76, v14
	v_add_f32_e32 v14, v77, v14
	v_cvt_pk_bf16_f32 v140, v72, v73
	v_cvt_pk_bf16_f32 v141, v74, v75
	ds_read_b64_tr_b16 v[164:165], v0 offset:31744
	ds_read_b64_tr_b16 v[166:167], v0 offset:32256
	v_mfma_f32_32x32x16_bf16 v[112:127], v[160:163], v[128:131], v[112:127]
	v_add_f32_e32 v0, v78, v14
	v_add_f32_e32 v0, v79, v0
	v_add_f32_e32 v0, 0, v0
	v_cvt_pk_bf16_f32 v142, v76, v77
	v_cvt_pk_bf16_f32 v143, v78, v79
	v_lshl_add_u64 v[14:15], v[220:221], 0, s[14:15]
	v_lshl_add_u64 v[64:65], v[14:15], 0, s[46:47]
	s_add_i32 s18, s1, s37
	s_mov_b32 s19, m0
	s_mov_b32 m0, s18
	s_nop 0
	global_load_lds_dwordx4 v[64:65], off
	s_mov_b32 m0, s19
	v_lshl_add_u64 v[200:201], v[222:223], 0, s[14:15]
	v_lshl_add_u64 v[64:65], v[200:201], 0, s[74:75]
	s_add_i32 s18, s25, s38
	s_mov_b32 s19, m0
	s_mov_b32 m0, s18
	s_nop 0
	global_load_lds_dwordx4 v[64:65], off
	s_mov_b32 m0, s19
	s_cmp_lt_u32 s48, 9
	s_mov_b64 s[18:19], -1
	s_cbranch_scc0 .LBB0_861
	s_cmp_lt_u32 s48, 3
	s_cbranch_scc0 .LBB0_858
; template<int MODE> __device__ __forceinline__ void hook(f32x16&p0,f32x16&p1,int t,int NT,int qrel,int hi,lds_fptr tab,int dbase,int ibase){
;     ...
;     const int delta=dbase-t;
;     if(delta<0||delta>8){
;       #pragma unroll
;       for(int r=0;r<16;++r){p0[r]=NEGBIG;p1[r]=NEGBIG;}
;     } else if(delta>=3){ const float cf=tab[256];
;       #pragma unroll
;       for(int r=0;r<16;++r){p0[r]+=cf;p1[r]+=cf;}
;     } else { const int ib=64*delta+ibase-4*hi;
;       #pragma unroll
;       for(int r=0;r<16;++r){ const int kc=(r&3)+8*(r>>2); int i0=ib-kc, i1=ib-32-kc; i0=i0>256?256:i0; i1=i1>256?256:i1; p0[r]+=tab[i0]; p1[r]+=tab[i1]; }
;     }
	v_min_u32_e32 v65, 0x120, v202
	s_add_i32 s18, 0, 0x15000
	v_min_u32_e32 v66, 0x101, v202
	v_min_u32_e32 v67, 0x121, v202
	v_min_u32_e32 v68, 0x102, v202
	v_min_u32_e32 v69, 0x122, v202
	v_min_u32_e32 v70, 0x103, v202
	v_min_u32_e32 v71, 0x123, v202
	v_min_u32_e32 v64, 0x100, v202
	v_lshl_add_u32 v65, v65, 2, s18
	v_lshlrev_b32_e32 v66, 2, v66
	v_lshl_add_u32 v67, v67, 2, s18
	v_lshlrev_b32_e32 v68, 2, v68
	v_lshl_add_u32 v69, v69, 2, s18
	v_lshlrev_b32_e32 v70, 2, v70
	v_lshl_add_u32 v71, v71, 2, s18
	v_lshl_add_u32 v64, v64, 2, s18
	v_add_u32_e32 v65, 0xffffff80, v65
	v_add3_u32 v66, s18, v66, -4
	v_add_u32_e32 v67, 0xffffff7c, v67
	v_add3_u32 v68, s18, v68, -8
	v_add_u32_e32 v69, 0xffffff78, v69
	v_add3_u32 v70, s18, v70, -12
	v_add_u32_e32 v71, 0xffffff74, v71
	ds_read_b32 v80, v64
	ds_read_b32 v64, v65
	ds_read_b32 v81, v66
	ds_read_b32 v65, v67
	ds_read_b32 v82, v68
	ds_read_b32 v66, v69
	ds_read_b32 v83, v70
	ds_read_b32 v67, v71
	v_min_u32_e32 v68, 0x108, v202
	v_min_u32_e32 v69, 0x128, v202
	v_min_u32_e32 v70, 0x109, v202
	v_min_u32_e32 v71, 0x129, v202
	v_min_u32_e32 v72, 0x10a, v202
	v_min_u32_e32 v73, 0x12a, v202
	v_min_u32_e32 v74, 0x10b, v202
	v_min_u32_e32 v75, 0x12b, v202
	v_lshl_add_u32 v68, v68, 2, s18
	v_lshl_add_u32 v69, v69, 2, s18
	v_lshl_add_u32 v70, v70, 2, s18
	v_lshl_add_u32 v71, v71, 2, s18
	v_lshl_add_u32 v72, v72, 2, s18
	v_lshl_add_u32 v73, v73, 2, s18
	v_lshl_add_u32 v74, v74, 2, s18
	v_lshl_add_u32 v75, v75, 2, s18
	v_subrev_u32_e32 v68, 32, v68
	v_add_u32_e32 v69, 0xffffff60, v69
	v_subrev_u32_e32 v70, 36, v70
	v_add_u32_e32 v71, 0xffffff5c, v71
	v_subrev_u32_e32 v72, 40, v72
	v_add_u32_e32 v73, 0xffffff58, v73
	v_subrev_u32_e32 v74, 44, v74
	v_add_u32_e32 v75, 0xffffff54, v75
	ds_read_b32 v84, v68
	ds_read_b32 v68, v69
	ds_read_b32 v85, v70
	ds_read_b32 v69, v71
	ds_read_b32 v86, v72
	ds_read_b32 v70, v73
	ds_read_b32 v87, v74
	ds_read_b32 v71, v75
	v_min_u32_e32 v72, 0x110, v202
	v_min_u32_e32 v73, 0x130, v202
	v_min_u32_e32 v74, 0x111, v202
	v_min_u32_e32 v75, 0x131, v202
	v_min_u32_e32 v76, 0x112, v202
	v_min_u32_e32 v77, 0x132, v202
	v_min_u32_e32 v79, 0x133, v202
	v_min_u32_e32 v92, 0x11a, v202
	v_lshl_add_u32 v72, v72, 2, s18
	v_lshl_add_u32 v73, v73, 2, s18
	v_lshl_add_u32 v74, v74, 2, s18
	v_lshl_add_u32 v75, v75, 2, s18
	v_lshl_add_u32 v76, v76, 2, s18
	v_lshl_add_u32 v77, v77, 2, s18
	v_min_u32_e32 v78, 0x113, v202
	v_lshl_add_u32 v79, v79, 2, s18
	v_min_u32_e32 v93, 0x13a, v202
	v_lshl_add_u32 v92, v92, 2, s18
	v_subrev_u32_e32 v72, 64, v72
	v_add_u32_e32 v73, 0xffffff40, v73
	v_add_u32_e32 v74, 0xffffffbc, v74
	v_add_u32_e32 v75, 0xffffff3c, v75
	v_add_u32_e32 v76, 0xffffffb8, v76
	v_add_u32_e32 v77, 0xffffff38, v77
	v_lshl_add_u32 v78, v78, 2, s18
	v_add_u32_e32 v79, 0xffffff34, v79
	v_add_u32_e32 v94, 0xffffff98, v92
	v_lshl_add_u32 v92, v93, 2, s18
	v_add_u32_e32 v78, 0xffffffb4, v78
	ds_read_b32 v88, v72
	ds_read_b32 v72, v73
	ds_read_b32 v89, v74
	ds_read_b32 v73, v75
	ds_read_b32 v90, v76
	ds_read_b32 v74, v77
	ds_read_b32 v91, v78
	ds_read_b32 v75, v79
	v_min_u32_e32 v76, 0x118, v202
	v_min_u32_e32 v77, 0x138, v202
	v_min_u32_e32 v79, 0x139, v202
	v_add_u32_e32 v93, 0xffffff18, v92
	v_min_u32_e32 v92, 0x11b, v202
	v_lshl_add_u32 v76, v76, 2, s18
	v_lshl_add_u32 v77, v77, 2, s18
	v_min_u32_e32 v78, 0x119, v202
	v_lshl_add_u32 v79, v79, 2, s18
	v_min_u32_e32 v95, 0x13b, v202
	v_lshl_add_u32 v92, v92, 2, s18
	v_add_u32_e32 v76, 0xffffffa0, v76
	v_add_u32_e32 v77, 0xffffff20, v77
	v_lshl_add_u32 v78, v78, 2, s18
	v_add_u32_e32 v79, 0xffffff1c, v79
	v_add_u32_e32 v160, 0xffffff94, v92
	v_lshl_add_u32 v92, v95, 2, s18
	v_add_u32_e32 v78, 0xffffff9c, v78
	v_add_u32_e32 v161, 0xffffff14, v92
	ds_read_b32 v92, v76
	ds_read_b32 v76, v77
	ds_read_b32 v77, v79
	ds_read_b32 v94, v94
	ds_read_b32 v79, v93
	ds_read_b32 v95, v160
	ds_read_b32 v160, v161
	ds_read_b32 v93, v78
	s_waitcnt lgkmcnt(14)
	v_add_f32_e32 v64, v112, v64
	v_add_f32_e32 v65, v113, v65
	v_add_f32_e32 v66, v114, v66
	v_add_f32_e32 v67, v115, v67
	v_add_f32_e32 v68, v116, v68
	v_add_f32_e32 v69, v117, v69
	v_add_f32_e32 v70, v118, v70
	v_add_f32_e32 v71, v119, v71
	s_waitcnt lgkmcnt(12)
	v_add_f32_e32 v72, v120, v72
	v_add_f32_e32 v73, v121, v73
	s_waitcnt lgkmcnt(8)
	v_add_f32_e32 v74, v122, v74
	v_add_f32_e32 v75, v123, v75
	s_waitcnt lgkmcnt(5)
	v_add_f32_e32 v76, v124, v76
	v_add_f32_e32 v77, v125, v77
	s_waitcnt lgkmcnt(3)
	v_add_f32_e32 v78, v126, v79
	s_waitcnt lgkmcnt(2)
	v_add_f32_e32 v94, v110, v94
	v_add_f32_e32 v95, v111, v95
	s_waitcnt lgkmcnt(0)
	v_add_f32_e32 v92, v108, v92
	v_add_f32_e32 v93, v109, v93
	v_add_f32_e32 v90, v106, v90
	v_add_f32_e32 v91, v107, v91
	v_add_f32_e32 v88, v104, v88
	v_add_f32_e32 v89, v105, v89
	v_add_f32_e32 v86, v102, v86
	v_add_f32_e32 v87, v103, v87
	v_add_f32_e32 v84, v100, v84
	v_add_f32_e32 v85, v101, v85
	v_add_f32_e32 v82, v98, v82
	v_add_f32_e32 v83, v99, v83
	v_add_f32_e32 v80, v96, v80
	v_add_f32_e32 v81, v97, v81
	v_add_f32_e32 v79, v127, v160
	s_mov_b64 s[18:19], 0

.LBB0_866:
	s_add_i32 s18, s25, 0x2000
	s_cmpk_lg_i32 s25, 0x4000
	s_cselect_b32 s44, s18, 0
	v_add_u32_e32 v0, s1, v251
	ds_read_b64_tr_b16 v[168:169], v0 offset:24576
	ds_read_b64_tr_b16 v[170:171], v0 offset:25088
	s_waitcnt lgkmcnt(9)
	v_mfma_f32_32x32x16_bf16 v[96:111], v[112:115], v[148:151], v[48:63]
	v_add_f32_e32 v2, v80, v81
	v_add_f32_e32 v2, v82, v2
	v_add_f32_e32 v2, v83, v2
	v_add_f32_e32 v2, v84, v2
	v_add_f32_e32 v2, v85, v2
	v_cvt_pk_bf16_f32 v156, v80, v81
	v_cvt_pk_bf16_f32 v157, v82, v83
	ds_read_b64_tr_b16 v[164:165], v0 offset:28672
	ds_read_b64_tr_b16 v[166:167], v0 offset:29184
	s_waitcnt lgkmcnt(10)
	v_mfma_f32_32x32x16_bf16 v[112:127], v[160:163], v[148:151], v[48:63]
	v_add_f32_e32 v2, v86, v2
	v_add_f32_e32 v2, v87, v2
	v_add_f32_e32 v2, v88, v2
	v_add_f32_e32 v2, v89, v2
	v_cvt_pk_bf16_f32 v158, v84, v85
	v_cvt_pk_bf16_f32 v159, v86, v87
	ds_read_b64_tr_b16 v[10:11], v0 offset:25600
	ds_read_b64_tr_b16 v[12:13], v0 offset:26112
	s_waitcnt lgkmcnt(11)
	v_mfma_f32_32x32x16_bf16 v[96:111], v[192:195], v[136:139], v[96:111]
	v_add_f32_e32 v2, v90, v2
	v_add_f32_e32 v2, v91, v2
	v_add_f32_e32 v2, v92, v2
	v_add_f32_e32 v2, v93, v2
	v_cvt_pk_bf16_f32 v152, v88, v89
	v_cvt_pk_bf16_f32 v153, v90, v91
	ds_read_b64_tr_b16 v[160:161], v0 offset:29696
	ds_read_b64_tr_b16 v[162:163], v0 offset:30208
	s_waitcnt lgkmcnt(12)
	v_mfma_f32_32x32x16_bf16 v[112:127], v[188:191], v[136:139], v[112:127]
	v_add_f32_e32 v2, v94, v2
	v_add_f32_e32 v2, v95, v2
	v_add_f32_e32 v2, v64, v2
	v_add_f32_e32 v2, v65, v2
	v_cvt_pk_bf16_f32 v154, v92, v93
	v_cvt_pk_bf16_f32 v155, v94, v95
	ds_read_b64_tr_b16 v[196:197], v0 offset:26624
	ds_read_b64_tr_b16 v[198:199], v0 offset:27136
	s_waitcnt lgkmcnt(13)
	v_mfma_f32_32x32x16_bf16 v[96:111], v[184:187], v[132:135], v[96:111]
	v_add_f32_e32 v2, v66, v2
	v_add_f32_e32 v2, v67, v2
	v_add_f32_e32 v2, v68, v2
	v_add_f32_e32 v6, v69, v2
	v_cvt_pk_bf16_f32 v144, v64, v65
	v_cvt_pk_bf16_f32 v145, v66, v67
	ds_read_b64_tr_b16 v[2:3], v0 offset:30720
	ds_read_b64_tr_b16 v[4:5], v0 offset:31232
	s_waitcnt lgkmcnt(14)
	v_mfma_f32_32x32x16_bf16 v[112:127], v[180:183], v[132:135], v[112:127]
	v_add_f32_e32 v6, v70, v6
	v_add_f32_e32 v6, v71, v6
	v_add_f32_e32 v6, v72, v6
	v_add_f32_e32 v64, v73, v6
	v_cvt_pk_bf16_f32 v146, v68, v69
	v_cvt_pk_bf16_f32 v147, v70, v71
	ds_read_b64_tr_b16 v[6:7], v0 offset:27648
	ds_read_b64_tr_b16 v[8:9], v0 offset:28160
	s_waitcnt lgkmcnt(14)
	v_mfma_f32_32x32x16_bf16 v[96:111], v[176:179], v[128:131], v[96:111]
	v_add_f32_e32 v64, v74, v64
	v_add_f32_e32 v64, v75, v64
	v_add_f32_e32 v64, v76, v64
	v_add_f32_e32 v64, v77, v64
	v_cvt_pk_bf16_f32 v140, v72, v73
	v_cvt_pk_bf16_f32 v141, v74, v75
	ds_read_b64_tr_b16 v[192:193], v0 offset:31744
	ds_read_b64_tr_b16 v[194:195], v0 offset:32256
	v_mfma_f32_32x32x16_bf16 v[112:127], v[172:175], v[128:131], v[112:127]
	v_add_f32_e32 v0, v78, v64
	v_add_f32_e32 v0, v79, v0
	v_add_f32_e32 v0, 0, v0
	v_cvt_pk_bf16_f32 v142, v76, v77
	v_cvt_pk_bf16_f32 v143, v78, v79
	v_lshl_add_u64 v[14:15], v[14:15], 0, s[66:67]
	s_add_i32 s1, s25, s37
	s_mov_b32 s18, m0
	s_mov_b32 m0, s1
	s_nop 0
	global_load_lds_dwordx4 v[14:15], off
	s_mov_b32 m0, s18
	v_lshl_add_u64 v[14:15], v[200:201], 0, s[86:87]
	s_add_i32 s1, s44, s38
	s_mov_b32 s18, m0
	s_mov_b32 m0, s1
	s_nop 0
	global_load_lds_dwordx4 v[14:15], off
	s_mov_b32 m0, s18
	s_add_i32 s1, s48, -1
	s_cmp_lt_u32 s1, 9
	s_mov_b64 s[18:19], -1
	s_cbranch_scc0 .LBB0_872
	s_cmp_lt_u32 s1, 3
	s_cbranch_scc0 .LBB0_869
; template<int MODE> __device__ __forceinline__ void hook(f32x16&p0,f32x16&p1,int t,int NT,int qrel,int hi,lds_fptr tab,int dbase,int ibase){
;     ...
;     const int delta=dbase-t;
;     if(delta<0||delta>8){
;       #pragma unroll
;       for(int r=0;r<16;++r){p0[r]=NEGBIG;p1[r]=NEGBIG;}
;     } else if(delta>=3){ const float cf=tab[256];
;       #pragma unroll
;       for(int r=0;r<16;++r){p0[r]+=cf;p1[r]+=cf;}
;     } else { const int ib=64*delta+ibase-4*hi;
;       #pragma unroll
;       for(int r=0;r<16;++r){ const int kc=(r&3)+8*(r>>2); int i0=ib-kc, i1=ib-32-kc; i0=i0>256?256:i0; i1=i1>256?256:i1; p0[r]+=tab[i0]; p1[r]+=tab[i1]; }
;     }
	v_subrev_u32_e32 v76, 64, v202
	v_min_u32_e32 v64, 0x101, v76
	s_add_i32 s1, 0, 0x15000
	v_min_u32_e32 v65, 0x121, v76
	v_lshlrev_b32_e32 v64, 2, v64
	v_add3_u32 v66, s1, v64, -4
	v_lshl_add_u32 v64, v65, 2, s1
	v_add_u32_e32 v67, 0xffffff7c, v64
	v_min_u32_e32 v64, 0x102, v76
	v_min_u32_e32 v65, 0x122, v76
	v_lshlrev_b32_e32 v64, 2, v64
	v_add3_u32 v68, s1, v64, -8
	v_lshl_add_u32 v64, v65, 2, s1
	v_add_u32_e32 v69, 0xffffff78, v64
	v_min_u32_e32 v64, 0x103, v76
	v_min_u32_e32 v15, 0x120, v76
	v_min_u32_e32 v65, 0x123, v76
	v_lshlrev_b32_e32 v64, 2, v64
	v_min_u32_e32 v14, 0x100, v76
	v_lshl_add_u32 v15, v15, 2, s1
	v_add3_u32 v70, s1, v64, -12
	v_lshl_add_u32 v64, v65, 2, s1
	v_lshl_add_u32 v14, v14, 2, s1
	v_add_u32_e32 v15, 0xffffff80, v15
	v_add_u32_e32 v71, 0xffffff74, v64
	ds_read_b32 v64, v14
	ds_read_b32 v14, v15
	ds_read_b32 v65, v66
	ds_read_b32 v15, v67
	ds_read_b32 v80, v68
	ds_read_b32 v66, v69
	ds_read_b32 v81, v70
	ds_read_b32 v67, v71
	v_min_u32_e32 v68, 0x108, v76
	v_min_u32_e32 v69, 0x128, v76
	v_min_u32_e32 v70, 0x109, v76
	v_min_u32_e32 v71, 0x129, v76
	v_min_u32_e32 v72, 0x10a, v76
	v_min_u32_e32 v73, 0x12a, v76
	v_min_u32_e32 v74, 0x10b, v76
	v_min_u32_e32 v75, 0x12b, v76
	v_lshl_add_u32 v68, v68, 2, s1
	v_lshl_add_u32 v69, v69, 2, s1
	v_lshl_add_u32 v70, v70, 2, s1
	v_lshl_add_u32 v71, v71, 2, s1
	v_lshl_add_u32 v72, v72, 2, s1
	v_lshl_add_u32 v73, v73, 2, s1
	v_lshl_add_u32 v74, v74, 2, s1
	v_lshl_add_u32 v75, v75, 2, s1
	v_subrev_u32_e32 v68, 32, v68
	v_add_u32_e32 v69, 0xffffff60, v69
	v_subrev_u32_e32 v70, 36, v70
	v_add_u32_e32 v71, 0xffffff5c, v71
	v_subrev_u32_e32 v72, 40, v72
	v_add_u32_e32 v73, 0xffffff58, v73
	v_subrev_u32_e32 v74, 44, v74
	v_add_u32_e32 v75, 0xffffff54, v75
	ds_read_b32 v82, v68
	ds_read_b32 v68, v69
	ds_read_b32 v83, v70
	ds_read_b32 v69, v71
	ds_read_b32 v84, v72
	ds_read_b32 v70, v73
	ds_read_b32 v85, v74
	ds_read_b32 v71, v75
	v_min_u32_e32 v72, 0x110, v76
	v_min_u32_e32 v73, 0x130, v76
	v_min_u32_e32 v74, 0x111, v76
	v_min_u32_e32 v75, 0x131, v76
	v_min_u32_e32 v86, 0x133, v76
	v_lshl_add_u32 v72, v72, 2, s1
	v_lshl_add_u32 v73, v73, 2, s1
	v_lshl_add_u32 v74, v74, 2, s1
	v_lshl_add_u32 v75, v75, 2, s1
	v_min_u32_e32 v77, 0x112, v76
	v_min_u32_e32 v78, 0x132, v76
	v_min_u32_e32 v79, 0x113, v76
	v_lshl_add_u32 v86, v86, 2, s1
	v_subrev_u32_e32 v72, 64, v72
	v_add_u32_e32 v73, 0xffffff40, v73
	v_add_u32_e32 v74, 0xffffffbc, v74
	v_add_u32_e32 v75, 0xffffff3c, v75
	v_lshl_add_u32 v77, v77, 2, s1
	v_lshl_add_u32 v78, v78, 2, s1
	v_lshl_add_u32 v79, v79, 2, s1
	v_add_u32_e32 v90, 0xffffff34, v86
	v_add_u32_e32 v77, 0xffffffb8, v77
	v_add_u32_e32 v78, 0xffffff38, v78
	v_add_u32_e32 v79, 0xffffffb4, v79
	ds_read_b32 v86, v72
	ds_read_b32 v72, v73
	ds_read_b32 v87, v74
	ds_read_b32 v73, v75
	ds_read_b32 v88, v77
	ds_read_b32 v74, v78
	ds_read_b32 v89, v79
	ds_read_b32 v75, v90
	v_min_u32_e32 v90, 0x139, v76
	v_lshl_add_u32 v90, v90, 2, s1
	v_add_u32_e32 v91, 0xffffff1c, v90
	v_min_u32_e32 v90, 0x11a, v76
	v_min_u32_e32 v92, 0x13a, v76
	v_lshl_add_u32 v90, v90, 2, s1
	v_add_u32_e32 v93, 0xffffff98, v90
	v_lshl_add_u32 v90, v92, 2, s1
	v_min_u32_e32 v77, 0x118, v76
	v_min_u32_e32 v78, 0x138, v76
	v_min_u32_e32 v79, 0x119, v76
	v_add_u32_e32 v94, 0xffffff18, v90
	v_min_u32_e32 v90, 0x11b, v76
	v_min_u32_e32 v76, 0x13b, v76
	v_lshl_add_u32 v77, v77, 2, s1
	v_lshl_add_u32 v78, v78, 2, s1
	v_lshl_add_u32 v76, v76, 2, s1
	v_add_u32_e32 v77, 0xffffffa0, v77
	v_add_u32_e32 v78, 0xffffff20, v78
	v_lshl_add_u32 v79, v79, 2, s1
	v_lshl_add_u32 v90, v90, 2, s1
	v_add_u32_e32 v172, 0xffffff14, v76
	v_add_u32_e32 v79, 0xffffff9c, v79
	v_add_u32_e32 v95, 0xffffff94, v90
	ds_read_b32 v90, v77
	ds_read_b32 v76, v78
	ds_read_b32 v77, v91
	ds_read_b32 v92, v93
	ds_read_b32 v78, v94
	ds_read_b32 v93, v95
	ds_read_b32 v172, v172
	ds_read_b32 v91, v79
	s_waitcnt lgkmcnt(14)
	v_add_f32_e32 v14, v112, v14
	v_add_f32_e32 v15, v113, v15
	v_add_f32_e32 v66, v114, v66
	v_add_f32_e32 v67, v115, v67
	v_add_f32_e32 v68, v116, v68
	v_add_f32_e32 v69, v117, v69
	v_add_f32_e32 v70, v118, v70
	v_add_f32_e32 v71, v119, v71
	s_waitcnt lgkmcnt(12)
	v_add_f32_e32 v72, v120, v72
	v_add_f32_e32 v73, v121, v73
	s_waitcnt lgkmcnt(8)
	v_add_f32_e32 v74, v122, v74
	v_add_f32_e32 v75, v123, v75
	s_waitcnt lgkmcnt(5)
	v_add_f32_e32 v76, v124, v76
	v_add_f32_e32 v77, v125, v77
	s_waitcnt lgkmcnt(3)
	v_add_f32_e32 v78, v126, v78
	s_waitcnt lgkmcnt(2)
	v_add_f32_e32 v94, v110, v92
	v_add_f32_e32 v95, v111, v93
	s_waitcnt lgkmcnt(0)
	v_add_f32_e32 v92, v108, v90
	v_add_f32_e32 v93, v109, v91
	v_add_f32_e32 v90, v106, v88
	v_add_f32_e32 v91, v107, v89
	v_add_f32_e32 v88, v104, v86
	v_add_f32_e32 v89, v105, v87
	v_add_f32_e32 v86, v102, v84
	v_add_f32_e32 v87, v103, v85
	v_add_f32_e32 v84, v100, v82
	v_add_f32_e32 v85, v101, v83
	v_add_f32_e32 v82, v98, v80
	v_add_f32_e32 v83, v99, v81
	v_add_f32_e32 v80, v96, v64
	v_add_f32_e32 v81, v97, v65
	v_add_f32_e32 v79, v127, v172
	s_mov_b64 s[18:19], 0

; template<int MODE> __device__ __forceinline__ void hook(f32x16&p0,f32x16&p1,int t,int NT,int qrel,int hi,lds_fptr tab,int dbase,int ibase){
;     ...
;     const int delta=dbase-t;
;     if(delta<0||delta>8){
;       #pragma unroll
;       for(int r=0;r<16;++r){p0[r]=NEGBIG;p1[r]=NEGBIG;}
;     } else if(delta>=3){ const float cf=tab[256];
;       #pragma unroll
;       for(int r=0;r<16;++r){p0[r]+=cf;p1[r]+=cf;}
;     } else { const int ib=64*delta+ibase-4*hi;
;       #pragma unroll
;       for(int r=0;r<16;++r){ const int kc=(r&3)+8*(r>>2); int i0=ib-kc, i1=ib-32-kc; i0=i0>256?256:i0; i1=i1>256?256:i1; p0[r]+=tab[i0]; p1[r]+=tab[i1]; }
;     }
.LBB0_890:
	v_lshl_add_u64 v[14:15], v[222:223], 0, s[18:19]
	v_lshl_add_u64 v[64:65], v[14:15], 0, s[50:51]
	s_add_i32 s6, s40, s38
	s_mov_b32 s7, m0
	s_mov_b32 m0, s6
	s_nop 0
	global_load_lds_dwordx4 v[64:65], off
	s_mov_b32 m0, s7
	s_add_i32 s20, s48, 1
	s_cmp_lt_u32 s20, 9
	s_mov_b64 s[6:7], -1
	s_cbranch_scc0 .LBB0_896
	s_cmp_lt_u32 s20, 3
	s_cbranch_scc0 .LBB0_893
	v_add_u32_e32 v64, s49, v254
	v_add_u32_e32 v76, 0x80, v64
	v_min_u32_e32 v65, 0x120, v76
	s_add_i32 s6, 0, 0x15000
	v_min_u32_e32 v66, 0x101, v76
	v_min_u32_e32 v67, 0x121, v76
	v_min_u32_e32 v68, 0x102, v76
	v_min_u32_e32 v69, 0x122, v76
	v_min_u32_e32 v70, 0x103, v76
	v_min_u32_e32 v71, 0x123, v76
	v_min_u32_e32 v64, 0x100, v76
	v_lshl_add_u32 v65, v65, 2, s6
	v_lshlrev_b32_e32 v66, 2, v66
	v_lshl_add_u32 v67, v67, 2, s6
	v_lshlrev_b32_e32 v68, 2, v68
	v_lshl_add_u32 v69, v69, 2, s6
	v_lshlrev_b32_e32 v70, 2, v70
	v_lshl_add_u32 v71, v71, 2, s6
	v_lshl_add_u32 v64, v64, 2, s6
	v_add_u32_e32 v65, 0xffffff80, v65
	v_add3_u32 v66, s6, v66, -4
	v_add_u32_e32 v67, 0xffffff7c, v67
	v_add3_u32 v68, s6, v68, -8
	v_add_u32_e32 v69, 0xffffff78, v69
	v_add3_u32 v70, s6, v70, -12
	v_add_u32_e32 v71, 0xffffff74, v71
	ds_read_b32 v80, v64
	ds_read_b32 v64, v65
	ds_read_b32 v81, v66
	ds_read_b32 v65, v67
	ds_read_b32 v82, v68
	ds_read_b32 v66, v69
	ds_read_b32 v83, v70
	ds_read_b32 v67, v71
	v_min_u32_e32 v68, 0x108, v76
	v_min_u32_e32 v69, 0x128, v76
	v_min_u32_e32 v70, 0x109, v76
	v_min_u32_e32 v71, 0x129, v76
	v_min_u32_e32 v72, 0x10a, v76
	v_min_u32_e32 v73, 0x12a, v76
	v_min_u32_e32 v74, 0x10b, v76
	v_min_u32_e32 v75, 0x12b, v76
	v_lshl_add_u32 v68, v68, 2, s6
	v_lshl_add_u32 v69, v69, 2, s6
	v_lshl_add_u32 v70, v70, 2, s6
	v_lshl_add_u32 v71, v71, 2, s6
	v_lshl_add_u32 v72, v72, 2, s6
	v_lshl_add_u32 v73, v73, 2, s6
	v_lshl_add_u32 v74, v74, 2, s6
	v_lshl_add_u32 v75, v75, 2, s6
	v_subrev_u32_e32 v68, 32, v68
	v_add_u32_e32 v69, 0xffffff60, v69
	v_subrev_u32_e32 v70, 36, v70
	v_add_u32_e32 v71, 0xffffff5c, v71
	v_subrev_u32_e32 v72, 40, v72
	v_add_u32_e32 v73, 0xffffff58, v73
	v_subrev_u32_e32 v74, 44, v74
	v_add_u32_e32 v75, 0xffffff54, v75
	ds_read_b32 v84, v68
	ds_read_b32 v68, v69
	ds_read_b32 v85, v70
	ds_read_b32 v69, v71
	ds_read_b32 v86, v72
	ds_read_b32 v70, v73
	ds_read_b32 v87, v74
	ds_read_b32 v71, v75
	v_min_u32_e32 v72, 0x110, v76
	v_min_u32_e32 v73, 0x130, v76
	v_min_u32_e32 v74, 0x111, v76
	v_min_u32_e32 v75, 0x131, v76
	v_min_u32_e32 v88, 0x133, v76
	v_lshl_add_u32 v72, v72, 2, s6
	v_lshl_add_u32 v73, v73, 2, s6
	v_lshl_add_u32 v74, v74, 2, s6
	v_lshl_add_u32 v75, v75, 2, s6
	v_min_u32_e32 v77, 0x112, v76
	v_min_u32_e32 v78, 0x132, v76
	v_min_u32_e32 v79, 0x113, v76
	v_lshl_add_u32 v88, v88, 2, s6
	v_subrev_u32_e32 v72, 64, v72
	v_add_u32_e32 v73, 0xffffff40, v73
	v_add_u32_e32 v74, 0xffffffbc, v74
	v_add_u32_e32 v75, 0xffffff3c, v75
	v_lshl_add_u32 v77, v77, 2, s6
	v_lshl_add_u32 v78, v78, 2, s6
	v_lshl_add_u32 v79, v79, 2, s6
	v_add_u32_e32 v92, 0xffffff34, v88
	v_add_u32_e32 v77, 0xffffffb8, v77
	v_add_u32_e32 v78, 0xffffff38, v78
	v_add_u32_e32 v79, 0xffffffb4, v79
	ds_read_b32 v88, v72
	ds_read_b32 v72, v73
	ds_read_b32 v89, v74
	ds_read_b32 v73, v75
	ds_read_b32 v90, v77
	ds_read_b32 v74, v78
	ds_read_b32 v91, v79
	ds_read_b32 v75, v92
	v_min_u32_e32 v92, 0x139, v76
	v_lshl_add_u32 v92, v92, 2, s6
	v_add_u32_e32 v93, 0xffffff1c, v92
	v_min_u32_e32 v92, 0x11a, v76
	v_min_u32_e32 v94, 0x13a, v76
	v_lshl_add_u32 v92, v92, 2, s6
	v_min_u32_e32 v77, 0x118, v76
	v_min_u32_e32 v78, 0x138, v76
	v_add_u32_e32 v95, 0xffffff98, v92
	v_lshl_add_u32 v92, v94, 2, s6
	v_lshl_add_u32 v77, v77, 2, s6
	v_lshl_add_u32 v78, v78, 2, s6
	v_min_u32_e32 v79, 0x119, v76
	v_add_u32_e32 v160, 0xffffff18, v92
	v_min_u32_e32 v92, 0x11b, v76
	v_min_u32_e32 v76, 0x13b, v76
	v_add_u32_e32 v77, 0xffffffa0, v77
	v_add_u32_e32 v78, 0xffffff20, v78
	v_lshl_add_u32 v79, v79, 2, s6
	v_lshl_add_u32 v92, v92, 2, s6
	v_lshl_add_u32 v76, v76, 2, s6
	v_add_u32_e32 v79, 0xffffff9c, v79
	v_add_u32_e32 v161, 0xffffff94, v92
	v_add_u32_e32 v162, 0xffffff14, v76
	ds_read_b32 v92, v77
	ds_read_b32 v76, v78
	ds_read_b32 v77, v93
	ds_read_b32 v94, v95
	ds_read_b32 v78, v160
	ds_read_b32 v95, v161
	ds_read_b32 v160, v162
	ds_read_b32 v93, v79
	s_waitcnt lgkmcnt(14)
	v_add_f32_e32 v64, v112, v64
	v_add_f32_e32 v65, v113, v65
	v_add_f32_e32 v66, v114, v66
	v_add_f32_e32 v67, v115, v67
	v_add_f32_e32 v68, v116, v68
	v_add_f32_e32 v69, v117, v69
	v_add_f32_e32 v70, v118, v70
	v_add_f32_e32 v71, v119, v71
	s_waitcnt lgkmcnt(12)
	v_add_f32_e32 v72, v120, v72
	v_add_f32_e32 v73, v121, v73
	s_waitcnt lgkmcnt(8)
	v_add_f32_e32 v74, v122, v74
	v_add_f32_e32 v75, v123, v75
	s_waitcnt lgkmcnt(5)
	v_add_f32_e32 v76, v124, v76
	v_add_f32_e32 v77, v125, v77
	s_waitcnt lgkmcnt(3)
	v_add_f32_e32 v78, v126, v78
	s_waitcnt lgkmcnt(2)
	v_add_f32_e32 v94, v110, v94
	v_add_f32_e32 v95, v111, v95
	s_waitcnt lgkmcnt(0)
	v_add_f32_e32 v92, v108, v92
	v_add_f32_e32 v93, v109, v93
	v_add_f32_e32 v90, v106, v90
	v_add_f32_e32 v91, v107, v91
	v_add_f32_e32 v88, v104, v88
	v_add_f32_e32 v89, v105, v89
	v_add_f32_e32 v86, v102, v86
	v_add_f32_e32 v87, v103, v87
	v_add_f32_e32 v84, v100, v84
	v_add_f32_e32 v85, v101, v85
	v_add_f32_e32 v82, v98, v82
	v_add_f32_e32 v83, v99, v83
	v_add_f32_e32 v80, v96, v80
	v_add_f32_e32 v81, v97, v81
	v_add_f32_e32 v79, v127, v160
	s_mov_b64 s[6:7], 0

; template<int MODE> __device__ __forceinline__ void hook(f32x16&p0,f32x16&p1,int t,int NT,int qrel,int hi,lds_fptr tab,int dbase,int ibase){
;     ...
;     const int delta=dbase-t;
;     if(delta<0||delta>8){
;       #pragma unroll
;       for(int r=0;r<16;++r){p0[r]=NEGBIG;p1[r]=NEGBIG;}
;     } else if(delta>=3){ const float cf=tab[256];
;       #pragma unroll
;       for(int r=0;r<16;++r){p0[r]+=cf;p1[r]+=cf;}
;     } else { const int ib=64*delta+ibase-4*hi;
;       #pragma unroll
;       for(int r=0;r<16;++r){ const int kc=(r&3)+8*(r>>2); int i0=ib-kc, i1=ib-32-kc; i0=i0>256?256:i0; i1=i1>256?256:i1; p0[r]+=tab[i0]; p1[r]+=tab[i1]; }
;     }
.LBB0_911:
	s_cmp_lt_u32 s48, 9
	s_mov_b64 s[6:7], -1
	s_cbranch_scc0 .LBB0_919
	s_cmp_lt_u32 s48, 3
	s_cbranch_scc0 .LBB0_914
	v_add3_u32 v76, v254, s49, 64
	v_min_u32_e32 v64, 0x101, v76
	s_add_i32 s1, 0, 0x15000
	v_min_u32_e32 v65, 0x121, v76
	v_lshlrev_b32_e32 v64, 2, v64
	v_add3_u32 v66, s1, v64, -4
	v_lshl_add_u32 v64, v65, 2, s1
	v_add_u32_e32 v67, 0xffffff7c, v64
	v_min_u32_e32 v64, 0x102, v76
	v_min_u32_e32 v65, 0x122, v76
	v_lshlrev_b32_e32 v64, 2, v64
	v_add3_u32 v68, s1, v64, -8
	v_lshl_add_u32 v64, v65, 2, s1
	v_add_u32_e32 v69, 0xffffff78, v64
	v_min_u32_e32 v64, 0x103, v76
	v_min_u32_e32 v15, 0x120, v76
	v_min_u32_e32 v65, 0x123, v76
	v_lshlrev_b32_e32 v64, 2, v64
	v_min_u32_e32 v14, 0x100, v76
	v_lshl_add_u32 v15, v15, 2, s1
	v_add3_u32 v70, s1, v64, -12
	v_lshl_add_u32 v64, v65, 2, s1
	v_lshl_add_u32 v14, v14, 2, s1
	v_add_u32_e32 v15, 0xffffff80, v15
	v_add_u32_e32 v71, 0xffffff74, v64
	ds_read_b32 v64, v14
	ds_read_b32 v14, v15
	ds_read_b32 v65, v66
	ds_read_b32 v15, v67
	ds_read_b32 v80, v68
	ds_read_b32 v66, v69
	ds_read_b32 v81, v70
	ds_read_b32 v67, v71
	v_min_u32_e32 v68, 0x108, v76
	v_min_u32_e32 v69, 0x128, v76
	v_min_u32_e32 v70, 0x109, v76
	v_min_u32_e32 v71, 0x129, v76
	v_min_u32_e32 v72, 0x10a, v76
	v_min_u32_e32 v73, 0x12a, v76
	v_min_u32_e32 v74, 0x10b, v76
	v_min_u32_e32 v75, 0x12b, v76
	v_lshl_add_u32 v68, v68, 2, s1
	v_lshl_add_u32 v69, v69, 2, s1
	v_lshl_add_u32 v70, v70, 2, s1
	v_lshl_add_u32 v71, v71, 2, s1
	v_lshl_add_u32 v72, v72, 2, s1
	v_lshl_add_u32 v73, v73, 2, s1
	v_lshl_add_u32 v74, v74, 2, s1
	v_lshl_add_u32 v75, v75, 2, s1
	v_subrev_u32_e32 v68, 32, v68
	v_add_u32_e32 v69, 0xffffff60, v69
	v_subrev_u32_e32 v70, 36, v70
	v_add_u32_e32 v71, 0xffffff5c, v71
	v_subrev_u32_e32 v72, 40, v72
	v_add_u32_e32 v73, 0xffffff58, v73
	v_subrev_u32_e32 v74, 44, v74
	v_add_u32_e32 v75, 0xffffff54, v75
	ds_read_b32 v82, v68
	ds_read_b32 v68, v69
	ds_read_b32 v83, v70
	ds_read_b32 v69, v71
	ds_read_b32 v84, v72
	ds_read_b32 v70, v73
	ds_read_b32 v85, v74
	ds_read_b32 v71, v75
	v_min_u32_e32 v72, 0x110, v76
	v_min_u32_e32 v73, 0x130, v76
	v_min_u32_e32 v74, 0x111, v76
	v_min_u32_e32 v75, 0x131, v76
	v_min_u32_e32 v86, 0x133, v76
	v_lshl_add_u32 v72, v72, 2, s1
	v_lshl_add_u32 v73, v73, 2, s1
	v_lshl_add_u32 v74, v74, 2, s1
	v_lshl_add_u32 v75, v75, 2, s1
	v_min_u32_e32 v77, 0x112, v76
	v_min_u32_e32 v78, 0x132, v76
	v_min_u32_e32 v79, 0x113, v76
	v_lshl_add_u32 v86, v86, 2, s1
	v_subrev_u32_e32 v72, 64, v72
	v_add_u32_e32 v73, 0xffffff40, v73
	v_add_u32_e32 v74, 0xffffffbc, v74
	v_add_u32_e32 v75, 0xffffff3c, v75
	v_lshl_add_u32 v77, v77, 2, s1
	v_lshl_add_u32 v78, v78, 2, s1
	v_lshl_add_u32 v79, v79, 2, s1
	v_add_u32_e32 v90, 0xffffff34, v86
	v_add_u32_e32 v77, 0xffffffb8, v77
	v_add_u32_e32 v78, 0xffffff38, v78
	v_add_u32_e32 v79, 0xffffffb4, v79
	ds_read_b32 v86, v72
	ds_read_b32 v72, v73
	ds_read_b32 v87, v74
	ds_read_b32 v73, v75
	ds_read_b32 v88, v77
	ds_read_b32 v74, v78
	ds_read_b32 v89, v79
	ds_read_b32 v75, v90
	v_min_u32_e32 v90, 0x139, v76
	v_lshl_add_u32 v90, v90, 2, s1
	v_add_u32_e32 v91, 0xffffff1c, v90
	v_min_u32_e32 v90, 0x11a, v76
	v_min_u32_e32 v92, 0x13a, v76
	v_lshl_add_u32 v90, v90, 2, s1
	v_add_u32_e32 v93, 0xffffff98, v90
	v_lshl_add_u32 v90, v92, 2, s1
	v_min_u32_e32 v77, 0x118, v76
	v_min_u32_e32 v78, 0x138, v76
	v_min_u32_e32 v79, 0x119, v76
	v_add_u32_e32 v94, 0xffffff18, v90
	v_min_u32_e32 v90, 0x11b, v76
	v_min_u32_e32 v76, 0x13b, v76
	v_lshl_add_u32 v77, v77, 2, s1
	v_lshl_add_u32 v78, v78, 2, s1
	v_lshl_add_u32 v76, v76, 2, s1
	v_add_u32_e32 v77, 0xffffffa0, v77
	v_add_u32_e32 v78, 0xffffff20, v78
	v_lshl_add_u32 v79, v79, 2, s1
	v_lshl_add_u32 v90, v90, 2, s1
	v_add_u32_e32 v212, 0xffffff14, v76
	v_add_u32_e32 v79, 0xffffff9c, v79
	v_add_u32_e32 v95, 0xffffff94, v90
	ds_read_b32 v90, v77
	ds_read_b32 v76, v78
	ds_read_b32 v77, v91
	ds_read_b32 v92, v93
	ds_read_b32 v78, v94
	ds_read_b32 v93, v95
	ds_read_b32 v212, v212
	ds_read_b32 v91, v79
	s_waitcnt lgkmcnt(14)
	v_add_f32_e32 v14, v112, v14
	v_add_f32_e32 v15, v113, v15
	v_add_f32_e32 v66, v114, v66
	v_add_f32_e32 v67, v115, v67
	v_add_f32_e32 v68, v116, v68
	v_add_f32_e32 v69, v117, v69
	v_add_f32_e32 v70, v118, v70
	v_add_f32_e32 v71, v119, v71
	s_waitcnt lgkmcnt(12)
	v_add_f32_e32 v72, v120, v72
	v_add_f32_e32 v73, v121, v73
	s_waitcnt lgkmcnt(8)
	v_add_f32_e32 v74, v122, v74
	v_add_f32_e32 v75, v123, v75
	s_waitcnt lgkmcnt(5)
	v_add_f32_e32 v76, v124, v76
	v_add_f32_e32 v77, v125, v77
	s_waitcnt lgkmcnt(3)
	v_add_f32_e32 v78, v126, v78
	s_waitcnt lgkmcnt(2)
	v_add_f32_e32 v94, v110, v92
	v_add_f32_e32 v95, v111, v93
	s_waitcnt lgkmcnt(0)
	v_add_f32_e32 v92, v108, v90
	v_add_f32_e32 v93, v109, v91
	v_add_f32_e32 v90, v106, v88
	v_add_f32_e32 v91, v107, v89
	v_add_f32_e32 v88, v104, v86
	v_add_f32_e32 v89, v105, v87
	v_add_f32_e32 v86, v102, v84
	v_add_f32_e32 v87, v103, v85
	v_add_f32_e32 v84, v100, v82
	v_add_f32_e32 v85, v101, v83
	v_add_f32_e32 v82, v98, v80
	v_add_f32_e32 v83, v99, v81
	v_add_f32_e32 v80, v96, v64
	v_add_f32_e32 v81, v97, v65
	v_add_f32_e32 v79, v127, v212
	s_mov_b64 s[6:7], 0

.LBB0_949:
	v_add_u32_e32 v0, s40, v251
	ds_read_b64_tr_b16 v[6:7], v0 offset:24576
	ds_read_b64_tr_b16 v[8:9], v0 offset:25088
	s_waitcnt lgkmcnt(9)
	v_mfma_f32_32x32x16_bf16 v[96:111], v[188:191], v[148:151], v[48:63]
	v_add_f32_e32 v2, v80, v81
	v_add_f32_e32 v2, v82, v2
	v_add_f32_e32 v2, v83, v2
	v_add_f32_e32 v2, v84, v2
	v_add_f32_e32 v10, v85, v2
	v_cvt_pk_bf16_f32 v156, v80, v81
	v_cvt_pk_bf16_f32 v157, v82, v83
	ds_read_b64_tr_b16 v[2:3], v0 offset:28672
	ds_read_b64_tr_b16 v[4:5], v0 offset:29184
	s_waitcnt lgkmcnt(10)
	v_mfma_f32_32x32x16_bf16 v[48:63], v[184:187], v[148:151], v[48:63]
	v_add_f32_e32 v10, v86, v10
	v_add_f32_e32 v10, v87, v10
	v_add_f32_e32 v10, v88, v10
	v_add_f32_e32 v14, v89, v10
	v_cvt_pk_bf16_f32 v158, v84, v85
	v_cvt_pk_bf16_f32 v159, v86, v87
	ds_read_b64_tr_b16 v[10:11], v0 offset:25600
	ds_read_b64_tr_b16 v[12:13], v0 offset:26112
	s_waitcnt lgkmcnt(11)
	v_mfma_f32_32x32x16_bf16 v[96:111], v[180:183], v[136:139], v[96:111]
	v_add_f32_e32 v14, v90, v14
	v_add_f32_e32 v14, v91, v14
	v_add_f32_e32 v14, v92, v14
	v_add_f32_e32 v14, v93, v14
	v_cvt_pk_bf16_f32 v152, v88, v89
	v_cvt_pk_bf16_f32 v153, v90, v91
	ds_read_b64_tr_b16 v[112:113], v0 offset:29696
	ds_read_b64_tr_b16 v[114:115], v0 offset:30208
	s_waitcnt lgkmcnt(12)
	v_mfma_f32_32x32x16_bf16 v[48:63], v[176:179], v[136:139], v[48:63]
	v_add_f32_e32 v14, v94, v14
	v_add_f32_e32 v14, v95, v14
	v_add_f32_e32 v14, v64, v14
	v_add_f32_e32 v14, v65, v14
	v_cvt_pk_bf16_f32 v154, v92, v93
	v_cvt_pk_bf16_f32 v155, v94, v95
	ds_read_b64_tr_b16 v[124:125], v0 offset:26624
	ds_read_b64_tr_b16 v[126:127], v0 offset:27136
	s_waitcnt lgkmcnt(13)
	v_mfma_f32_32x32x16_bf16 v[96:111], v[172:175], v[132:135], v[96:111]
	v_add_f32_e32 v14, v66, v14
	v_add_f32_e32 v14, v67, v14
	v_add_f32_e32 v14, v68, v14
	v_add_f32_e32 v14, v69, v14
	v_cvt_pk_bf16_f32 v144, v64, v65
	v_cvt_pk_bf16_f32 v145, v66, v67
	ds_read_b64_tr_b16 v[92:93], v0 offset:30720
	ds_read_b64_tr_b16 v[94:95], v0 offset:31232
	s_waitcnt lgkmcnt(14)
	v_mfma_f32_32x32x16_bf16 v[48:63], v[168:171], v[132:135], v[48:63]
	v_add_f32_e32 v14, v70, v14
	v_add_f32_e32 v14, v71, v14
	v_add_f32_e32 v14, v72, v14
	v_add_f32_e32 v14, v73, v14
	v_cvt_pk_bf16_f32 v146, v68, v69
	v_cvt_pk_bf16_f32 v147, v70, v71
	ds_read_b64_tr_b16 v[116:117], v0 offset:27648
	ds_read_b64_tr_b16 v[118:119], v0 offset:28160
	s_waitcnt lgkmcnt(14)
	v_mfma_f32_32x32x16_bf16 v[96:111], v[164:167], v[128:131], v[96:111]
	v_add_f32_e32 v14, v74, v14
	v_add_f32_e32 v14, v75, v14
	v_add_f32_e32 v14, v76, v14
	v_add_f32_e32 v14, v77, v14
	v_cvt_pk_bf16_f32 v140, v72, v73
	v_cvt_pk_bf16_f32 v141, v74, v75
	ds_read_b64_tr_b16 v[120:121], v0 offset:31744
	ds_read_b64_tr_b16 v[122:123], v0 offset:32256
	v_mfma_f32_32x32x16_bf16 v[48:63], v[160:163], v[128:131], v[48:63]
	v_add_f32_e32 v0, v78, v14
	v_add_f32_e32 v0, v79, v0
	v_add_f32_e32 v0, 0, v0
	v_cvt_pk_bf16_f32 v142, v76, v77
	v_cvt_pk_bf16_f32 v143, v78, v79
	s_sub_i32 s1, s36, s39
	s_add_i32 s1, s1, 1
	s_cmp_lt_u32 s1, 9
	s_mov_b64 s[4:5], -1
	s_cbranch_scc0 .LBB0_955
	s_cmp_lt_u32 s1, 3
	s_cbranch_scc0 .LBB0_952
; template<int MODE> __device__ __forceinline__ void hook(f32x16&p0,f32x16&p1,int t,int NT,int qrel,int hi,lds_fptr tab,int dbase,int ibase){
;     ...
;     const int delta=dbase-t;
;     if(delta<0||delta>8){
;       #pragma unroll
;       for(int r=0;r<16;++r){p0[r]=NEGBIG;p1[r]=NEGBIG;}
;     } else if(delta>=3){ const float cf=tab[256];
;       #pragma unroll
;       for(int r=0;r<16;++r){p0[r]+=cf;p1[r]+=cf;}
;     } else { const int ib=64*delta+ibase-4*hi;
;       #pragma unroll
;       for(int r=0;r<16;++r){ const int kc=(r&3)+8*(r>>2); int i0=ib-kc, i1=ib-32-kc; i0=i0>256?256:i0; i1=i1>256?256:i1; p0[r]+=tab[i0]; p1[r]+=tab[i1]; }
;     }
	v_lshlrev_b32_e32 v14, 2, v243
	v_sub_u32_e32 v14, v248, v14
	v_lshl_add_u32 v74, s1, 6, v14
	v_min_u32_e32 v15, 0x120, v74
	s_add_i32 s1, 0, 0x15000
	v_min_u32_e32 v64, 0x101, v74
	v_min_u32_e32 v65, 0x121, v74
	v_min_u32_e32 v66, 0x102, v74
	v_min_u32_e32 v67, 0x122, v74
	v_min_u32_e32 v68, 0x103, v74
	v_min_u32_e32 v69, 0x123, v74
	v_min_u32_e32 v14, 0x100, v74
	v_lshl_add_u32 v15, v15, 2, s1
	v_lshlrev_b32_e32 v64, 2, v64
	v_lshl_add_u32 v65, v65, 2, s1
	v_lshlrev_b32_e32 v66, 2, v66
	v_lshl_add_u32 v67, v67, 2, s1
	v_lshlrev_b32_e32 v68, 2, v68
	v_lshl_add_u32 v69, v69, 2, s1
	v_lshl_add_u32 v14, v14, 2, s1
	v_add_u32_e32 v15, 0xffffff80, v15
	v_add3_u32 v64, s1, v64, -4
	v_add_u32_e32 v65, 0xffffff7c, v65
	v_add3_u32 v66, s1, v66, -8
	v_add_u32_e32 v67, 0xffffff78, v67
	v_add3_u32 v68, s1, v68, -12
	v_add_u32_e32 v69, 0xffffff74, v69
	ds_read_b32 v76, v14
	ds_read_b32 v14, v15
	ds_read_b32 v77, v64
	ds_read_b32 v15, v65
	ds_read_b32 v78, v66
	ds_read_b32 v64, v67
	ds_read_b32 v79, v68
	ds_read_b32 v65, v69
	v_min_u32_e32 v66, 0x108, v74
	v_min_u32_e32 v67, 0x128, v74
	v_min_u32_e32 v68, 0x109, v74
	v_min_u32_e32 v69, 0x129, v74
	v_min_u32_e32 v70, 0x10a, v74
	v_min_u32_e32 v71, 0x12a, v74
	v_min_u32_e32 v72, 0x10b, v74
	v_min_u32_e32 v73, 0x12b, v74
	v_lshl_add_u32 v66, v66, 2, s1
	v_lshl_add_u32 v67, v67, 2, s1
	v_lshl_add_u32 v68, v68, 2, s1
	v_lshl_add_u32 v69, v69, 2, s1
	v_lshl_add_u32 v70, v70, 2, s1
	v_lshl_add_u32 v71, v71, 2, s1
	v_lshl_add_u32 v72, v72, 2, s1
	v_lshl_add_u32 v73, v73, 2, s1
	v_min_u32_e32 v84, 0x132, v74
	v_subrev_u32_e32 v66, 32, v66
	v_add_u32_e32 v67, 0xffffff60, v67
	v_subrev_u32_e32 v68, 36, v68
	v_add_u32_e32 v69, 0xffffff5c, v69
	v_subrev_u32_e32 v70, 40, v70
	v_add_u32_e32 v71, 0xffffff58, v71
	v_subrev_u32_e32 v72, 44, v72
	v_add_u32_e32 v73, 0xffffff54, v73
	v_lshl_add_u32 v84, v84, 2, s1
	ds_read_b32 v80, v66
	ds_read_b32 v66, v67
	ds_read_b32 v81, v68
	ds_read_b32 v67, v69
	ds_read_b32 v82, v70
	ds_read_b32 v68, v71
	ds_read_b32 v83, v72
	ds_read_b32 v69, v73
	v_min_u32_e32 v70, 0x110, v74
	v_min_u32_e32 v71, 0x130, v74
	v_min_u32_e32 v72, 0x111, v74
	v_min_u32_e32 v73, 0x131, v74
	v_min_u32_e32 v75, 0x112, v74
	v_add_u32_e32 v87, 0xffffff38, v84
	v_min_u32_e32 v84, 0x113, v74
	v_lshl_add_u32 v70, v70, 2, s1
	v_lshl_add_u32 v71, v71, 2, s1
	v_lshl_add_u32 v72, v72, 2, s1
	v_lshl_add_u32 v73, v73, 2, s1
	v_lshl_add_u32 v75, v75, 2, s1
	v_min_u32_e32 v85, 0x133, v74
	v_lshl_add_u32 v84, v84, 2, s1
	v_subrev_u32_e32 v70, 64, v70
	v_add_u32_e32 v71, 0xffffff40, v71
	v_add_u32_e32 v72, 0xffffffbc, v72
	v_add_u32_e32 v73, 0xffffff3c, v73
	v_add_u32_e32 v75, 0xffffffb8, v75
	v_add_u32_e32 v88, 0xffffffb4, v84
	v_lshl_add_u32 v84, v85, 2, s1
	v_add_u32_e32 v89, 0xffffff34, v84
	ds_read_b32 v84, v70
	ds_read_b32 v70, v71
	ds_read_b32 v85, v72
	ds_read_b32 v71, v73
	ds_read_b32 v86, v75
	ds_read_b32 v72, v87
	ds_read_b32 v87, v88
	ds_read_b32 v73, v89
	v_min_u32_e32 v75, 0x119, v74
	v_min_u32_e32 v88, 0x139, v74
	v_lshl_add_u32 v75, v75, 2, s1
	v_add_u32_e32 v89, 0xffffff9c, v75
	v_lshl_add_u32 v75, v88, 2, s1
	v_min_u32_e32 v88, 0x11a, v74
	v_min_u32_e32 v90, 0x13a, v74
	v_lshl_add_u32 v88, v88, 2, s1
	v_add_u32_e32 v91, 0xffffff98, v88
	v_lshl_add_u32 v88, v90, 2, s1
	s_waitcnt lgkmcnt(14)
	v_add_f32_e32 v128, v50, v64
	v_add_f32_e32 v129, v51, v65
	s_waitcnt lgkmcnt(12)
	v_add_f32_e32 v64, v52, v66
	v_add_f32_e32 v65, v53, v67
	s_waitcnt lgkmcnt(8)
	v_add_f32_e32 v66, v54, v68
	v_add_f32_e32 v67, v55, v69
	s_waitcnt lgkmcnt(4)
	v_add_f32_e32 v68, v56, v70
	v_add_f32_e32 v69, v57, v71
	v_min_u32_e32 v70, 0x118, v74
	v_add_u32_e32 v130, 0xffffff18, v88
	v_min_u32_e32 v88, 0x11b, v74
	v_min_u32_e32 v71, 0x138, v74
	v_lshl_add_u32 v70, v70, 2, s1
	v_min_u32_e32 v74, 0x13b, v74
	v_lshl_add_u32 v88, v88, 2, s1
	v_add_u32_e32 v70, 0xffffffa0, v70
	v_lshl_add_u32 v71, v71, 2, s1
	v_add_u32_e32 v75, 0xffffff1c, v75
	v_add_u32_e32 v131, 0xffffff94, v88
	v_lshl_add_u32 v74, v74, 2, s1
	v_add_u32_e32 v71, 0xffffff20, v71
	v_add_u32_e32 v132, 0xffffff14, v74
	ds_read_b32 v88, v70
	ds_read_b32 v74, v71
	ds_read_b32 v75, v75
	ds_read_b32 v90, v91
	ds_read_b32 v130, v130
	ds_read_b32 v91, v131
	ds_read_b32 v131, v132
	ds_read_b32 v89, v89
	v_add_f32_e32 v14, v48, v14
	v_add_f32_e32 v15, v49, v15
	s_waitcnt lgkmcnt(8)
	v_add_f32_e32 v70, v58, v72
	v_add_f32_e32 v71, v59, v73
	s_waitcnt lgkmcnt(5)
	v_add_f32_e32 v72, v60, v74
	v_add_f32_e32 v73, v61, v75
	s_waitcnt lgkmcnt(3)
	v_add_f32_e32 v74, v62, v130
	s_waitcnt lgkmcnt(2)
	v_add_f32_e32 v90, v110, v90
	v_add_f32_e32 v91, v111, v91
	s_waitcnt lgkmcnt(0)
	v_add_f32_e32 v88, v108, v88
	v_add_f32_e32 v89, v109, v89
	v_add_f32_e32 v86, v106, v86
	v_add_f32_e32 v87, v107, v87
	v_add_f32_e32 v84, v104, v84
	v_add_f32_e32 v85, v105, v85
	v_add_f32_e32 v82, v102, v82
	v_add_f32_e32 v83, v103, v83
	v_add_f32_e32 v80, v100, v80
	v_add_f32_e32 v81, v101, v81
	v_add_f32_e32 v78, v98, v78
	v_add_f32_e32 v79, v99, v79
	v_add_f32_e32 v76, v96, v76
	v_add_f32_e32 v77, v97, v77
	v_add_f32_e32 v75, v63, v131
	s_mov_b64 s[4:5], 0
